# QG/KV GEMM epilogues: packed fp32 VALU ops (v_pk_mul/add/fma_f32) split into scalar pairs, bit-identical
# baseline (speedup 1.0000x reference)
.LBB0_237:
	s_andn2_b64 vcc, exec, s[42:43]
	v_and_b32_e32 v182, 0x1fcf, v170
	s_cbranch_vccnz .LBB0_239
	v_lshlrev_b32_e32 v148, 4, v182
	v_cndmask_b32_e64 v171, v230, v148, s[0:1]
	v_mul_f32_e32 v148, v146, v146
	v_mul_f32_e32 v149, v147, v147
	v_mul_f32_e32 v150, v144, v144
	v_mul_f32_e32 v151, v145, v145
	s_mov_b32 s0, 0x800000
	v_pk_mov_b32 v[172:173], v[150:151], v[148:149] op_sel:[1,0]
	v_mov_b32_e32 v151, v149
	v_add_f32_e32 v148, v172, v150
	v_add_f32_e32 v149, v173, v151
	v_mul_f32_e32 v150, v142, v142
	v_mul_f32_e32 v151, v143, v143
	v_mul_f32_e32 v172, v140, v140
	v_mul_f32_e32 v173, v141, v141
	v_add_f32_e32 v148, v148, v149
	v_mov_b32_e32 v149, v148
	v_pk_mov_b32 v[174:175], v[172:173], v[150:151] op_sel:[1,0]
	v_mov_b32_e32 v173, v151
	v_add_f32_e32 v150, v174, v172
	v_add_f32_e32 v151, v175, v173
	v_mul_f32_e32 v172, v132, v132
	v_mul_f32_e32 v173, v133, v133
	v_add_f32_e32 v150, v150, v151
	v_mov_b32_e32 v151, v150
	v_mov_b32_e32 v149, v172
	v_mov_b32_e32 v151, v173
	v_add_f32_e32 v148, v148, v150
	v_add_f32_e32 v149, v149, v151
	v_mul_f32_e32 v150, v137, v137
	v_mul_f32_e32 v172, v139, v139
	v_mul_f32_e32 v174, v134, v134
	v_mul_f32_e32 v175, v135, v135
	v_fma_f32 v151, v137, v137, v150
	v_fma_f32 v150, v136, v136, v150
	v_fma_f32 v173, v139, v139, v172
	v_fma_f32 v172, v138, v138, v172
	v_mov_b32_e32 v151, v174
	v_mov_b32_e32 v173, v175
	v_add_f32_e32 v150, v150, v172
	v_add_f32_e32 v151, v151, v173
	s_nop 0
	v_add_f32_e32 v148, v148, v150
	v_add_f32_e32 v149, v149, v151
	v_and_b32_e32 v150, 64, v229
	v_add_f32_e32 v148, v148, v149
	v_xor_b32_e32 v149, 16, v229
	v_add_u32_e32 v150, 64, v150
	v_cmp_lt_i32_e32 vcc, v149, v150
	s_nop 1
	v_cndmask_b32_e32 v149, v229, v149, vcc
	v_lshlrev_b32_e32 v149, 2, v149
	ds_bpermute_b32 v149, v149, v148
	s_waitcnt lgkmcnt(0)
	v_add_f32_e32 v148, v148, v149
	v_xor_b32_e32 v149, 32, v229
	v_cmp_lt_i32_e32 vcc, v149, v150
	s_nop 1
	v_cndmask_b32_e32 v149, v229, v149, vcc
	v_lshlrev_b32_e32 v149, 2, v149
	ds_bpermute_b32 v150, v149, v148
	s_waitcnt lgkmcnt(0)
	v_add_f32_e32 v148, v148, v150
	v_fmamk_f32 v148, v148, 0x3c800000, v226
	v_cmp_gt_f32_e32 vcc, s0, v148
	v_mul_f32_e32 v150, 0x4b800000, v148
	s_nop 0
	v_cndmask_b32_e32 v148, v148, v150, vcc
	v_rsq_f32_e32 v148, v148
	s_nop 0
	v_mul_f32_e32 v150, 0x45800000, v148
	v_cndmask_b32_e32 v148, v148, v150, vcc
	v_mul_f32_e32 v144, v144, v148
	v_mul_f32_e32 v145, v145, v148
	v_mul_f32_e32 v146, v146, v148
	v_mul_f32_e32 v147, v147, v148
	s_waitcnt vmcnt(0)
	v_mul_f32_e32 v172, v44, v144
	v_mul_f32_e32 v173, v45, v145
	v_lshlrev_b32_e32 v144, 2, v171
	v_mov_b32_e32 v145, v3
	v_mul_f32_e32 v174, v46, v146
	v_mul_f32_e32 v175, v47, v147
	v_lshl_add_u64 v[144:145], v[164:165], 0, v[144:145]
	v_mul_f32_e32 v140, v140, v148
	v_mul_f32_e32 v141, v141, v148
	v_mul_f32_e32 v142, v142, v148
	v_mul_f32_e32 v143, v143, v148
	v_mul_f32_e32 v136, v136, v148
	v_mul_f32_e32 v137, v137, v148
	v_mul_f32_e32 v138, v138, v148
	v_mul_f32_e32 v139, v139, v148
	v_mul_f32_e32 v132, v132, v148
	v_mul_f32_e32 v133, v133, v148
	v_mul_f32_e32 v134, v134, v148
	v_mul_f32_e32 v135, v135, v148
	ds_bpermute_b32 v178, v149, v172
	ds_bpermute_b32 v179, v149, v173
	ds_bpermute_b32 v176, v149, v174
	ds_bpermute_b32 v177, v149, v175
	global_load_dwordx4 v[148:151], v[144:145], off
	s_nop 0
	global_load_dwordx4 v[144:147], v[144:145], off offset:16
	v_mul_f32_e32 v142, v42, v142
	v_mul_f32_e32 v143, v43, v143
	v_mul_f32_e32 v140, v40, v140
	v_mul_f32_e32 v141, v41, v141
	v_mul_f32_e32 v138, v38, v138
	v_mul_f32_e32 v139, v39, v139
	v_mul_f32_e32 v136, v36, v136
	v_mul_f32_e32 v137, v37, v137
	v_mul_f32_e32 v134, v34, v134
	v_mul_f32_e32 v135, v35, v135
	v_mul_f32_e32 v132, v32, v132
	v_mul_f32_e32 v133, v33, v133
	s_waitcnt vmcnt(1)
	v_mov_b32_e32 v184, v149
	v_mov_b32_e32 v185, v151
	s_waitcnt lgkmcnt(2)
	v_mul_f32_e32 v178, v184, v178
	v_mul_f32_e32 v179, v185, v179
	s_waitcnt vmcnt(0)
	v_mov_b32_e32 v184, v145
	v_mov_b32_e32 v185, v147
	s_waitcnt lgkmcnt(0)
	v_mul_f32_e32 v176, v184, v176
	v_mul_f32_e32 v177, v185, v177
	v_xor_b32_e32 v149, 0x80000000, v178
	v_xor_b32_e32 v145, 0x80000000, v176
	v_xor_b32_e32 v147, 0x80000000, v177
	v_xor_b32_e32 v151, 0x80000000, v179
	v_cndmask_b32_e64 v179, v179, v151, s[4:5]
	v_cndmask_b32_e64 v178, v178, v149, s[4:5]
	v_cndmask_b32_e64 v177, v177, v147, s[4:5]
	v_cndmask_b32_e64 v176, v176, v145, s[4:5]
	v_mov_b32_e32 v145, v146
	v_mov_b32_e32 v149, v150
	v_fma_f32 v146, v144, v174, v176
	v_fma_f32 v147, v145, v175, v177
	v_fma_f32 v144, v148, v172, v178
	v_fma_f32 v145, v149, v173, v179

.LBB0_260:
	s_andn2_b64 vcc, exec, s[42:43]
	v_and_b32_e32 v146, 0x1fdf, v136
	s_cbranch_vccnz .LBB0_262
	v_lshlrev_b32_e32 v132, 4, v146
	v_cndmask_b32_e64 v137, v230, v132, s[0:1]
	v_mul_f32_e32 v132, v130, v130
	v_mul_f32_e32 v133, v131, v131
	v_mul_f32_e32 v134, v128, v128
	v_mul_f32_e32 v135, v129, v129
	s_mov_b32 s0, 0x800000
	v_pk_mov_b32 v[138:139], v[134:135], v[132:133] op_sel:[1,0]
	v_mov_b32_e32 v135, v133
	v_add_f32_e32 v132, v138, v134
	v_add_f32_e32 v133, v139, v135
	v_mul_f32_e32 v134, v126, v126
	v_mul_f32_e32 v135, v127, v127
	v_mul_f32_e32 v138, v124, v124
	v_mul_f32_e32 v139, v125, v125
	v_add_f32_e32 v132, v132, v133
	v_mov_b32_e32 v133, v132
	v_pk_mov_b32 v[140:141], v[138:139], v[134:135] op_sel:[1,0]
	v_mov_b32_e32 v139, v135
	v_add_f32_e32 v134, v140, v138
	v_add_f32_e32 v135, v141, v139
	v_mul_f32_e32 v138, v116, v116
	v_mul_f32_e32 v139, v117, v117
	v_add_f32_e32 v134, v134, v135
	v_mov_b32_e32 v135, v134
	v_mov_b32_e32 v133, v138
	v_mov_b32_e32 v135, v139
	v_add_f32_e32 v132, v132, v134
	v_add_f32_e32 v133, v133, v135
	v_mul_f32_e32 v134, v121, v121
	v_mul_f32_e32 v138, v123, v123
	v_mul_f32_e32 v140, v118, v118
	v_mul_f32_e32 v141, v119, v119
	v_fma_f32 v135, v121, v121, v134
	v_fma_f32 v134, v120, v120, v134
	v_fma_f32 v139, v123, v123, v138
	v_fma_f32 v138, v122, v122, v138
	v_mov_b32_e32 v135, v140
	v_mov_b32_e32 v139, v141
	v_add_f32_e32 v134, v134, v138
	v_add_f32_e32 v135, v135, v139
	s_nop 0
	v_add_f32_e32 v132, v132, v134
	v_add_f32_e32 v133, v133, v135
	v_and_b32_e32 v134, 64, v229
	v_add_f32_e32 v132, v132, v133
	v_xor_b32_e32 v133, 16, v229
	v_add_u32_e32 v134, 64, v134
	v_cmp_lt_i32_e32 vcc, v133, v134
	s_nop 1
	v_cndmask_b32_e32 v133, v229, v133, vcc
	v_lshlrev_b32_e32 v133, 2, v133
	ds_bpermute_b32 v133, v133, v132
	s_waitcnt lgkmcnt(0)
	v_add_f32_e32 v132, v132, v133
	v_xor_b32_e32 v133, 32, v229
	v_cmp_lt_i32_e32 vcc, v133, v134
	s_nop 1
	v_cndmask_b32_e32 v133, v229, v133, vcc
	v_lshlrev_b32_e32 v133, 2, v133
	ds_bpermute_b32 v134, v133, v132
	s_waitcnt lgkmcnt(0)
	v_add_f32_e32 v132, v132, v134
	v_fmamk_f32 v132, v132, 0x3c800000, v226
	v_cmp_gt_f32_e32 vcc, s0, v132
	v_mul_f32_e32 v134, 0x4b800000, v132
	s_nop 0
	v_cndmask_b32_e32 v132, v132, v134, vcc
	v_rsq_f32_e32 v132, v132
	s_nop 0
	v_mul_f32_e32 v134, 0x45800000, v132
	v_cndmask_b32_e32 v132, v132, v134, vcc
	v_mul_f32_e32 v128, v128, v132
	v_mul_f32_e32 v129, v129, v132
	v_mul_f32_e32 v130, v130, v132
	v_mul_f32_e32 v131, v131, v132
	s_waitcnt vmcnt(0)
	v_mul_f32_e32 v138, v44, v128
	v_mul_f32_e32 v139, v45, v129
	v_lshlrev_b32_e32 v128, 2, v137
	v_mov_b32_e32 v129, v3
	v_mul_f32_e32 v140, v46, v130
	v_mul_f32_e32 v141, v47, v131
	v_lshl_add_u64 v[128:129], v[164:165], 0, v[128:129]
	v_mul_f32_e32 v124, v124, v132
	v_mul_f32_e32 v125, v125, v132
	v_mul_f32_e32 v126, v126, v132
	v_mul_f32_e32 v127, v127, v132
	v_mul_f32_e32 v120, v120, v132
	v_mul_f32_e32 v121, v121, v132
	v_mul_f32_e32 v122, v122, v132
	v_mul_f32_e32 v123, v123, v132
	v_mul_f32_e32 v116, v116, v132
	v_mul_f32_e32 v117, v117, v132
	v_mul_f32_e32 v118, v118, v132
	v_mul_f32_e32 v119, v119, v132
	ds_bpermute_b32 v144, v133, v138
	ds_bpermute_b32 v145, v133, v139
	ds_bpermute_b32 v142, v133, v140
	ds_bpermute_b32 v143, v133, v141
	global_load_dwordx4 v[132:135], v[128:129], off
	s_nop 0
	global_load_dwordx4 v[128:131], v[128:129], off offset:16
	v_mul_f32_e32 v126, v42, v126
	v_mul_f32_e32 v127, v43, v127
	v_mul_f32_e32 v124, v40, v124
	v_mul_f32_e32 v125, v41, v125
	v_mul_f32_e32 v122, v38, v122
	v_mul_f32_e32 v123, v39, v123
	v_mul_f32_e32 v120, v36, v120
	v_mul_f32_e32 v121, v37, v121
	v_mul_f32_e32 v118, v34, v118
	v_mul_f32_e32 v119, v35, v119
	v_mul_f32_e32 v116, v32, v116
	v_mul_f32_e32 v117, v33, v117
	s_waitcnt vmcnt(1)
	v_mov_b32_e32 v148, v133
	v_mov_b32_e32 v149, v135
	s_waitcnt lgkmcnt(2)
	v_mul_f32_e32 v144, v148, v144
	v_mul_f32_e32 v145, v149, v145
	s_waitcnt vmcnt(0)
	v_mov_b32_e32 v148, v129
	v_mov_b32_e32 v149, v131
	s_waitcnt lgkmcnt(0)
	v_mul_f32_e32 v142, v148, v142
	v_mul_f32_e32 v143, v149, v143
	v_xor_b32_e32 v133, 0x80000000, v144
	v_xor_b32_e32 v129, 0x80000000, v142
	v_xor_b32_e32 v131, 0x80000000, v143
	v_xor_b32_e32 v135, 0x80000000, v145
	v_cndmask_b32_e64 v145, v145, v135, s[4:5]
	v_cndmask_b32_e64 v144, v144, v133, s[4:5]
	v_cndmask_b32_e64 v143, v143, v131, s[4:5]
	v_cndmask_b32_e64 v142, v142, v129, s[4:5]
	v_mov_b32_e32 v129, v130
	v_mov_b32_e32 v133, v134
	v_fma_f32 v130, v128, v140, v142
	v_fma_f32 v131, v129, v141, v143
	v_fma_f32 v128, v132, v138, v144
	v_fma_f32 v129, v133, v139, v145

.LBB0_283:
	s_andn2_b64 vcc, exec, s[42:43]
	v_and_b32_e32 v130, 0x1fef, v120
	s_cbranch_vccnz .LBB0_285
	v_lshlrev_b32_e32 v116, 4, v130
	v_cndmask_b32_e64 v121, v230, v116, s[0:1]
	v_mul_f32_e32 v116, v114, v114
	v_mul_f32_e32 v117, v115, v115
	v_mul_f32_e32 v118, v112, v112
	v_mul_f32_e32 v119, v113, v113
	s_mov_b32 s0, 0x800000
	v_pk_mov_b32 v[122:123], v[118:119], v[116:117] op_sel:[1,0]
	v_mov_b32_e32 v119, v117
	v_add_f32_e32 v116, v122, v118
	v_add_f32_e32 v117, v123, v119
	v_mul_f32_e32 v118, v110, v110
	v_mul_f32_e32 v119, v111, v111
	v_mul_f32_e32 v122, v108, v108
	v_mul_f32_e32 v123, v109, v109
	v_add_f32_e32 v116, v116, v117
	v_mov_b32_e32 v117, v116
	v_pk_mov_b32 v[124:125], v[122:123], v[118:119] op_sel:[1,0]
	v_mov_b32_e32 v123, v119
	v_add_f32_e32 v118, v124, v122
	v_add_f32_e32 v119, v125, v123
	v_mul_f32_e32 v122, v100, v100
	v_mul_f32_e32 v123, v101, v101
	v_add_f32_e32 v118, v118, v119
	v_mov_b32_e32 v119, v118
	v_mov_b32_e32 v117, v122
	v_mov_b32_e32 v119, v123
	v_add_f32_e32 v116, v116, v118
	v_add_f32_e32 v117, v117, v119
	v_mul_f32_e32 v118, v105, v105
	v_mul_f32_e32 v122, v107, v107
	v_mul_f32_e32 v124, v102, v102
	v_mul_f32_e32 v125, v103, v103
	v_fma_f32 v119, v105, v105, v118
	v_fma_f32 v118, v104, v104, v118
	v_fma_f32 v123, v107, v107, v122
	v_fma_f32 v122, v106, v106, v122
	v_mov_b32_e32 v119, v124
	v_mov_b32_e32 v123, v125
	v_add_f32_e32 v118, v118, v122
	v_add_f32_e32 v119, v119, v123
	s_nop 0
	v_add_f32_e32 v116, v116, v118
	v_add_f32_e32 v117, v117, v119
	v_and_b32_e32 v118, 64, v229
	v_add_f32_e32 v116, v116, v117
	v_xor_b32_e32 v117, 16, v229
	v_add_u32_e32 v118, 64, v118
	v_cmp_lt_i32_e32 vcc, v117, v118
	s_nop 1
	v_cndmask_b32_e32 v117, v229, v117, vcc
	v_lshlrev_b32_e32 v117, 2, v117
	ds_bpermute_b32 v117, v117, v116
	s_waitcnt lgkmcnt(0)
	v_add_f32_e32 v116, v116, v117
	v_xor_b32_e32 v117, 32, v229
	v_cmp_lt_i32_e32 vcc, v117, v118
	s_nop 1
	v_cndmask_b32_e32 v117, v229, v117, vcc
	v_lshlrev_b32_e32 v117, 2, v117
	ds_bpermute_b32 v118, v117, v116
	s_waitcnt lgkmcnt(0)
	v_add_f32_e32 v116, v116, v118
	v_fmamk_f32 v116, v116, 0x3c800000, v226
	v_cmp_gt_f32_e32 vcc, s0, v116
	v_mul_f32_e32 v118, 0x4b800000, v116
	s_nop 0
	v_cndmask_b32_e32 v116, v116, v118, vcc
	v_rsq_f32_e32 v116, v116
	s_nop 0
	v_mul_f32_e32 v118, 0x45800000, v116
	v_cndmask_b32_e32 v116, v116, v118, vcc
	v_mul_f32_e32 v112, v112, v116
	v_mul_f32_e32 v113, v113, v116
	v_mul_f32_e32 v114, v114, v116
	v_mul_f32_e32 v115, v115, v116
	s_waitcnt vmcnt(0)
	v_mul_f32_e32 v122, v44, v112
	v_mul_f32_e32 v123, v45, v113
	v_lshlrev_b32_e32 v112, 2, v121
	v_mov_b32_e32 v113, v3
	v_mul_f32_e32 v124, v46, v114
	v_mul_f32_e32 v125, v47, v115
	v_lshl_add_u64 v[112:113], v[164:165], 0, v[112:113]
	v_mul_f32_e32 v108, v108, v116
	v_mul_f32_e32 v109, v109, v116
	v_mul_f32_e32 v110, v110, v116
	v_mul_f32_e32 v111, v111, v116
	v_mul_f32_e32 v104, v104, v116
	v_mul_f32_e32 v105, v105, v116
	v_mul_f32_e32 v106, v106, v116
	v_mul_f32_e32 v107, v107, v116
	v_mul_f32_e32 v100, v100, v116
	v_mul_f32_e32 v101, v101, v116
	v_mul_f32_e32 v102, v102, v116
	v_mul_f32_e32 v103, v103, v116
	ds_bpermute_b32 v128, v117, v122
	ds_bpermute_b32 v129, v117, v123
	ds_bpermute_b32 v126, v117, v124
	ds_bpermute_b32 v127, v117, v125
	global_load_dwordx4 v[116:119], v[112:113], off
	s_nop 0
	global_load_dwordx4 v[112:115], v[112:113], off offset:16
	v_mul_f32_e32 v110, v42, v110
	v_mul_f32_e32 v111, v43, v111
	v_mul_f32_e32 v108, v40, v108
	v_mul_f32_e32 v109, v41, v109
	v_mul_f32_e32 v106, v38, v106
	v_mul_f32_e32 v107, v39, v107
	v_mul_f32_e32 v104, v36, v104
	v_mul_f32_e32 v105, v37, v105
	v_mul_f32_e32 v102, v34, v102
	v_mul_f32_e32 v103, v35, v103
	v_mul_f32_e32 v100, v32, v100
	v_mul_f32_e32 v101, v33, v101
	s_waitcnt vmcnt(1)
	v_mov_b32_e32 v132, v117
	v_mov_b32_e32 v133, v119
	s_waitcnt lgkmcnt(2)
	v_mul_f32_e32 v128, v132, v128
	v_mul_f32_e32 v129, v133, v129
	s_waitcnt vmcnt(0)
	v_mov_b32_e32 v132, v113
	v_mov_b32_e32 v133, v115
	s_waitcnt lgkmcnt(0)
	v_mul_f32_e32 v126, v132, v126
	v_mul_f32_e32 v127, v133, v127
	v_xor_b32_e32 v117, 0x80000000, v128
	v_xor_b32_e32 v113, 0x80000000, v126
	v_xor_b32_e32 v115, 0x80000000, v127
	v_xor_b32_e32 v119, 0x80000000, v129
	v_cndmask_b32_e64 v129, v129, v119, s[4:5]
	v_cndmask_b32_e64 v128, v128, v117, s[4:5]
	v_cndmask_b32_e64 v127, v127, v115, s[4:5]
	v_cndmask_b32_e64 v126, v126, v113, s[4:5]
	v_mov_b32_e32 v113, v114
	v_mov_b32_e32 v117, v118
	v_fma_f32 v114, v112, v124, v126
	v_fma_f32 v115, v113, v125, v127
	v_fma_f32 v112, v116, v122, v128
	v_fma_f32 v113, v117, v123, v129

.LBB0_306:
	s_andn2_b64 vcc, exec, s[42:43]
	v_and_b32_e32 v114, 0x1fff, v104
	s_cbranch_vccnz .LBB0_308
	v_lshlrev_b32_e32 v100, 4, v114
	v_cndmask_b32_e64 v105, v230, v100, s[0:1]
	v_mul_f32_e32 v100, v98, v98
	v_mul_f32_e32 v101, v99, v99
	v_mul_f32_e32 v102, v96, v96
	v_mul_f32_e32 v103, v97, v97
	s_mov_b32 s0, 0x800000
	v_pk_mov_b32 v[106:107], v[102:103], v[100:101] op_sel:[1,0]
	v_mov_b32_e32 v103, v101
	v_add_f32_e32 v100, v106, v102
	v_add_f32_e32 v101, v107, v103
	v_mul_f32_e32 v102, v94, v94
	v_mul_f32_e32 v103, v95, v95
	v_mul_f32_e32 v106, v92, v92
	v_mul_f32_e32 v107, v93, v93
	v_add_f32_e32 v100, v100, v101
	v_mov_b32_e32 v101, v100
	v_pk_mov_b32 v[108:109], v[106:107], v[102:103] op_sel:[1,0]
	v_mov_b32_e32 v107, v103
	v_add_f32_e32 v102, v108, v106
	v_add_f32_e32 v103, v109, v107
	v_mul_f32_e32 v106, v84, v84
	v_mul_f32_e32 v107, v85, v85
	v_add_f32_e32 v102, v102, v103
	v_mov_b32_e32 v103, v102
	v_mov_b32_e32 v101, v106
	v_mov_b32_e32 v103, v107
	v_add_f32_e32 v100, v100, v102
	v_add_f32_e32 v101, v101, v103
	v_mul_f32_e32 v102, v89, v89
	v_mul_f32_e32 v106, v91, v91
	v_mul_f32_e32 v108, v86, v86
	v_mul_f32_e32 v109, v87, v87
	v_fma_f32 v103, v89, v89, v102
	v_fma_f32 v102, v88, v88, v102
	v_fma_f32 v107, v91, v91, v106
	v_fma_f32 v106, v90, v90, v106
	v_mov_b32_e32 v103, v108
	v_mov_b32_e32 v107, v109
	v_add_f32_e32 v102, v102, v106
	v_add_f32_e32 v103, v103, v107
	s_nop 0
	v_add_f32_e32 v100, v100, v102
	v_add_f32_e32 v101, v101, v103
	v_and_b32_e32 v102, 64, v229
	v_add_f32_e32 v100, v100, v101
	v_xor_b32_e32 v101, 16, v229
	v_add_u32_e32 v102, 64, v102
	v_cmp_lt_i32_e32 vcc, v101, v102
	s_nop 1
	v_cndmask_b32_e32 v101, v229, v101, vcc
	v_lshlrev_b32_e32 v101, 2, v101
	ds_bpermute_b32 v101, v101, v100
	s_waitcnt lgkmcnt(0)
	v_add_f32_e32 v100, v100, v101
	v_xor_b32_e32 v101, 32, v229
	v_cmp_lt_i32_e32 vcc, v101, v102
	s_nop 1
	v_cndmask_b32_e32 v101, v229, v101, vcc
	v_lshlrev_b32_e32 v101, 2, v101
	ds_bpermute_b32 v102, v101, v100
	s_waitcnt lgkmcnt(0)
	v_add_f32_e32 v100, v100, v102
	v_fmamk_f32 v100, v100, 0x3c800000, v226
	v_cmp_gt_f32_e32 vcc, s0, v100
	v_mul_f32_e32 v102, 0x4b800000, v100
	s_nop 0
	v_cndmask_b32_e32 v100, v100, v102, vcc
	v_rsq_f32_e32 v100, v100
	s_nop 0
	v_mul_f32_e32 v102, 0x45800000, v100
	v_cndmask_b32_e32 v100, v100, v102, vcc
	v_mul_f32_e32 v96, v96, v100
	v_mul_f32_e32 v97, v97, v100
	v_mul_f32_e32 v98, v98, v100
	v_mul_f32_e32 v99, v99, v100
	s_waitcnt vmcnt(0)
	v_mul_f32_e32 v106, v44, v96
	v_mul_f32_e32 v107, v45, v97
	v_lshlrev_b32_e32 v96, 2, v105
	v_mov_b32_e32 v97, v3
	v_mul_f32_e32 v108, v46, v98
	v_mul_f32_e32 v109, v47, v99
	v_lshl_add_u64 v[96:97], v[164:165], 0, v[96:97]
	v_mul_f32_e32 v92, v92, v100
	v_mul_f32_e32 v93, v93, v100
	v_mul_f32_e32 v94, v94, v100
	v_mul_f32_e32 v95, v95, v100
	v_mul_f32_e32 v88, v88, v100
	v_mul_f32_e32 v89, v89, v100
	v_mul_f32_e32 v90, v90, v100
	v_mul_f32_e32 v91, v91, v100
	v_mul_f32_e32 v84, v84, v100
	v_mul_f32_e32 v85, v85, v100
	v_mul_f32_e32 v86, v86, v100
	v_mul_f32_e32 v87, v87, v100
	ds_bpermute_b32 v112, v101, v106
	ds_bpermute_b32 v113, v101, v107
	ds_bpermute_b32 v110, v101, v108
	ds_bpermute_b32 v111, v101, v109
	global_load_dwordx4 v[100:103], v[96:97], off
	s_nop 0
	global_load_dwordx4 v[96:99], v[96:97], off offset:16
	v_mul_f32_e32 v94, v42, v94
	v_mul_f32_e32 v95, v43, v95
	v_mul_f32_e32 v92, v40, v92
	v_mul_f32_e32 v93, v41, v93
	v_mul_f32_e32 v90, v38, v90
	v_mul_f32_e32 v91, v39, v91
	v_mul_f32_e32 v88, v36, v88
	v_mul_f32_e32 v89, v37, v89
	v_mul_f32_e32 v86, v34, v86
	v_mul_f32_e32 v87, v35, v87
	v_mul_f32_e32 v84, v32, v84
	v_mul_f32_e32 v85, v33, v85
	s_waitcnt vmcnt(1)
	v_mov_b32_e32 v116, v101
	v_mov_b32_e32 v117, v103
	s_waitcnt lgkmcnt(2)
	v_mul_f32_e32 v112, v116, v112
	v_mul_f32_e32 v113, v117, v113
	s_waitcnt vmcnt(0)
	v_mov_b32_e32 v116, v97
	v_mov_b32_e32 v117, v99
	s_waitcnt lgkmcnt(0)
	v_mul_f32_e32 v110, v116, v110
	v_mul_f32_e32 v111, v117, v111
	v_xor_b32_e32 v101, 0x80000000, v112
	v_xor_b32_e32 v97, 0x80000000, v110
	v_xor_b32_e32 v99, 0x80000000, v111
	v_xor_b32_e32 v103, 0x80000000, v113
	v_cndmask_b32_e64 v113, v113, v103, s[4:5]
	v_cndmask_b32_e64 v112, v112, v101, s[4:5]
	v_cndmask_b32_e64 v111, v111, v99, s[4:5]
	v_cndmask_b32_e64 v110, v110, v97, s[4:5]
	v_mov_b32_e32 v97, v98
	v_mov_b32_e32 v101, v102
	v_fma_f32 v98, v96, v108, v110
	v_fma_f32 v99, v97, v109, v111
	v_fma_f32 v96, v100, v106, v112
	v_fma_f32 v97, v101, v107, v113

.LBB0_329:
	s_andn2_b64 vcc, exec, s[42:43]
	v_and_b32_e32 v98, 0x1fcf, v88
	s_cbranch_vccnz .LBB0_331
	v_lshlrev_b32_e32 v84, 4, v98
	v_cndmask_b32_e64 v89, v230, v84, s[0:1]
	v_mul_f32_e32 v84, v82, v82
	v_mul_f32_e32 v85, v83, v83
	v_mul_f32_e32 v86, v80, v80
	v_mul_f32_e32 v87, v81, v81
	s_mov_b32 s0, 0x800000
	v_pk_mov_b32 v[90:91], v[86:87], v[84:85] op_sel:[1,0]
	v_mov_b32_e32 v87, v85
	v_add_f32_e32 v84, v90, v86
	v_add_f32_e32 v85, v91, v87
	v_mul_f32_e32 v86, v78, v78
	v_mul_f32_e32 v87, v79, v79
	v_mul_f32_e32 v90, v76, v76
	v_mul_f32_e32 v91, v77, v77
	v_add_f32_e32 v84, v84, v85
	v_mov_b32_e32 v85, v84
	v_pk_mov_b32 v[92:93], v[90:91], v[86:87] op_sel:[1,0]
	v_mov_b32_e32 v91, v87
	v_add_f32_e32 v86, v92, v90
	v_add_f32_e32 v87, v93, v91
	v_mul_f32_e32 v90, v68, v68
	v_mul_f32_e32 v91, v69, v69
	v_add_f32_e32 v86, v86, v87
	v_mov_b32_e32 v87, v86
	v_mov_b32_e32 v85, v90
	v_mov_b32_e32 v87, v91
	v_add_f32_e32 v84, v84, v86
	v_add_f32_e32 v85, v85, v87
	v_mul_f32_e32 v86, v73, v73
	v_mul_f32_e32 v90, v75, v75
	v_mul_f32_e32 v92, v70, v70
	v_mul_f32_e32 v93, v71, v71
	v_fma_f32 v87, v73, v73, v86
	v_fma_f32 v86, v72, v72, v86
	v_fma_f32 v91, v75, v75, v90
	v_fma_f32 v90, v74, v74, v90
	v_mov_b32_e32 v87, v92
	v_mov_b32_e32 v91, v93
	v_add_f32_e32 v86, v86, v90
	v_add_f32_e32 v87, v87, v91
	s_nop 0
	v_add_f32_e32 v84, v84, v86
	v_add_f32_e32 v85, v85, v87
	v_and_b32_e32 v86, 64, v229
	v_add_f32_e32 v84, v84, v85
	v_xor_b32_e32 v85, 16, v229
	v_add_u32_e32 v86, 64, v86
	v_cmp_lt_i32_e32 vcc, v85, v86
	s_nop 1
	v_cndmask_b32_e32 v85, v229, v85, vcc
	v_lshlrev_b32_e32 v85, 2, v85
	ds_bpermute_b32 v85, v85, v84
	s_waitcnt lgkmcnt(0)
	v_add_f32_e32 v84, v84, v85
	v_xor_b32_e32 v85, 32, v229
	v_cmp_lt_i32_e32 vcc, v85, v86
	s_nop 1
	v_cndmask_b32_e32 v85, v229, v85, vcc
	v_lshlrev_b32_e32 v85, 2, v85
	ds_bpermute_b32 v86, v85, v84
	s_waitcnt lgkmcnt(0)
	v_add_f32_e32 v84, v84, v86
	v_fmamk_f32 v84, v84, 0x3c800000, v226
	v_cmp_gt_f32_e32 vcc, s0, v84
	v_mul_f32_e32 v86, 0x4b800000, v84
	s_nop 0
	v_cndmask_b32_e32 v84, v84, v86, vcc
	v_rsq_f32_e32 v84, v84
	s_nop 0
	v_mul_f32_e32 v86, 0x45800000, v84
	v_cndmask_b32_e32 v84, v84, v86, vcc
	v_mul_f32_e32 v80, v80, v84
	v_mul_f32_e32 v81, v81, v84
	v_mul_f32_e32 v82, v82, v84
	v_mul_f32_e32 v83, v83, v84
	s_waitcnt vmcnt(0)
	v_mul_f32_e32 v90, v44, v80
	v_mul_f32_e32 v91, v45, v81
	v_lshlrev_b32_e32 v80, 2, v89
	v_mov_b32_e32 v81, v3
	v_mul_f32_e32 v92, v46, v82
	v_mul_f32_e32 v93, v47, v83
	v_lshl_add_u64 v[80:81], v[164:165], 0, v[80:81]
	v_mul_f32_e32 v76, v76, v84
	v_mul_f32_e32 v77, v77, v84
	v_mul_f32_e32 v78, v78, v84
	v_mul_f32_e32 v79, v79, v84
	v_mul_f32_e32 v72, v72, v84
	v_mul_f32_e32 v73, v73, v84
	v_mul_f32_e32 v74, v74, v84
	v_mul_f32_e32 v75, v75, v84
	v_mul_f32_e32 v68, v68, v84
	v_mul_f32_e32 v69, v69, v84
	v_mul_f32_e32 v70, v70, v84
	v_mul_f32_e32 v71, v71, v84
	ds_bpermute_b32 v96, v85, v90
	ds_bpermute_b32 v97, v85, v91
	ds_bpermute_b32 v94, v85, v92
	ds_bpermute_b32 v95, v85, v93
	global_load_dwordx4 v[84:87], v[80:81], off
	s_nop 0
	global_load_dwordx4 v[80:83], v[80:81], off offset:16
	v_mul_f32_e32 v78, v42, v78
	v_mul_f32_e32 v79, v43, v79
	v_mul_f32_e32 v76, v40, v76
	v_mul_f32_e32 v77, v41, v77
	v_mul_f32_e32 v74, v38, v74
	v_mul_f32_e32 v75, v39, v75
	v_mul_f32_e32 v72, v36, v72
	v_mul_f32_e32 v73, v37, v73
	v_mul_f32_e32 v70, v34, v70
	v_mul_f32_e32 v71, v35, v71
	v_mul_f32_e32 v68, v32, v68
	v_mul_f32_e32 v69, v33, v69
	s_waitcnt vmcnt(1)
	v_mov_b32_e32 v100, v85
	v_mov_b32_e32 v101, v87
	s_waitcnt lgkmcnt(2)
	v_mul_f32_e32 v96, v100, v96
	v_mul_f32_e32 v97, v101, v97
	s_waitcnt vmcnt(0)
	v_mov_b32_e32 v100, v81
	v_mov_b32_e32 v101, v83
	s_waitcnt lgkmcnt(0)
	v_mul_f32_e32 v94, v100, v94
	v_mul_f32_e32 v95, v101, v95
	v_xor_b32_e32 v85, 0x80000000, v96
	v_xor_b32_e32 v81, 0x80000000, v94
	v_xor_b32_e32 v83, 0x80000000, v95
	v_xor_b32_e32 v87, 0x80000000, v97
	v_cndmask_b32_e64 v97, v97, v87, s[4:5]
	v_cndmask_b32_e64 v96, v96, v85, s[4:5]
	v_cndmask_b32_e64 v95, v95, v83, s[4:5]
	v_cndmask_b32_e64 v94, v94, v81, s[4:5]
	v_mov_b32_e32 v81, v82
	v_mov_b32_e32 v85, v86
	v_fma_f32 v82, v80, v92, v94
	v_fma_f32 v83, v81, v93, v95
	v_fma_f32 v80, v84, v90, v96
	v_fma_f32 v81, v85, v91, v97

.LBB0_352:
	s_andn2_b64 vcc, exec, s[42:43]
	v_and_b32_e32 v82, 0x1fdf, v72
	s_cbranch_vccnz .LBB0_354
	v_lshlrev_b32_e32 v68, 4, v82
	v_cndmask_b32_e64 v73, v230, v68, s[0:1]
	v_mul_f32_e32 v68, v66, v66
	v_mul_f32_e32 v69, v67, v67
	v_mul_f32_e32 v70, v64, v64
	v_mul_f32_e32 v71, v65, v65
	s_mov_b32 s0, 0x800000
	v_pk_mov_b32 v[74:75], v[70:71], v[68:69] op_sel:[1,0]
	v_mov_b32_e32 v71, v69
	v_add_f32_e32 v68, v74, v70
	v_add_f32_e32 v69, v75, v71
	v_mul_f32_e32 v70, v62, v62
	v_mul_f32_e32 v71, v63, v63
	v_mul_f32_e32 v74, v60, v60
	v_mul_f32_e32 v75, v61, v61
	v_add_f32_e32 v68, v68, v69
	v_mov_b32_e32 v69, v68
	v_pk_mov_b32 v[76:77], v[74:75], v[70:71] op_sel:[1,0]
	v_mov_b32_e32 v75, v71
	v_add_f32_e32 v70, v76, v74
	v_add_f32_e32 v71, v77, v75
	v_mul_f32_e32 v74, v52, v52
	v_mul_f32_e32 v75, v53, v53
	v_add_f32_e32 v70, v70, v71
	v_mov_b32_e32 v71, v70
	v_mov_b32_e32 v69, v74
	v_mov_b32_e32 v71, v75
	v_add_f32_e32 v68, v68, v70
	v_add_f32_e32 v69, v69, v71
	v_mul_f32_e32 v70, v57, v57
	v_mul_f32_e32 v74, v59, v59
	v_mul_f32_e32 v76, v54, v54
	v_mul_f32_e32 v77, v55, v55
	v_fma_f32 v71, v57, v57, v70
	v_fma_f32 v70, v56, v56, v70
	v_fma_f32 v75, v59, v59, v74
	v_fma_f32 v74, v58, v58, v74
	v_mov_b32_e32 v71, v76
	v_mov_b32_e32 v75, v77
	v_add_f32_e32 v70, v70, v74
	v_add_f32_e32 v71, v71, v75
	s_nop 0
	v_add_f32_e32 v68, v68, v70
	v_add_f32_e32 v69, v69, v71
	v_and_b32_e32 v70, 64, v229
	v_add_f32_e32 v68, v68, v69
	v_xor_b32_e32 v69, 16, v229
	v_add_u32_e32 v70, 64, v70
	v_cmp_lt_i32_e32 vcc, v69, v70
	s_nop 1
	v_cndmask_b32_e32 v69, v229, v69, vcc
	v_lshlrev_b32_e32 v69, 2, v69
	ds_bpermute_b32 v69, v69, v68
	s_waitcnt lgkmcnt(0)
	v_add_f32_e32 v68, v68, v69
	v_xor_b32_e32 v69, 32, v229
	v_cmp_lt_i32_e32 vcc, v69, v70
	s_nop 1
	v_cndmask_b32_e32 v69, v229, v69, vcc
	v_lshlrev_b32_e32 v69, 2, v69
	ds_bpermute_b32 v70, v69, v68
	s_waitcnt lgkmcnt(0)
	v_add_f32_e32 v68, v68, v70
	v_fmamk_f32 v68, v68, 0x3c800000, v226
	v_cmp_gt_f32_e32 vcc, s0, v68
	v_mul_f32_e32 v70, 0x4b800000, v68
	s_nop 0
	v_cndmask_b32_e32 v68, v68, v70, vcc
	v_rsq_f32_e32 v68, v68
	s_nop 0
	v_mul_f32_e32 v70, 0x45800000, v68
	v_cndmask_b32_e32 v68, v68, v70, vcc
	v_mul_f32_e32 v64, v64, v68
	v_mul_f32_e32 v65, v65, v68
	v_mul_f32_e32 v66, v66, v68
	v_mul_f32_e32 v67, v67, v68
	s_waitcnt vmcnt(0)
	v_mul_f32_e32 v74, v44, v64
	v_mul_f32_e32 v75, v45, v65
	v_lshlrev_b32_e32 v64, 2, v73
	v_mov_b32_e32 v65, v3
	v_mul_f32_e32 v76, v46, v66
	v_mul_f32_e32 v77, v47, v67
	v_lshl_add_u64 v[64:65], v[164:165], 0, v[64:65]
	v_mul_f32_e32 v60, v60, v68
	v_mul_f32_e32 v61, v61, v68
	v_mul_f32_e32 v62, v62, v68
	v_mul_f32_e32 v63, v63, v68
	v_mul_f32_e32 v56, v56, v68
	v_mul_f32_e32 v57, v57, v68
	v_mul_f32_e32 v58, v58, v68
	v_mul_f32_e32 v59, v59, v68
	v_mul_f32_e32 v52, v52, v68
	v_mul_f32_e32 v53, v53, v68
	v_mul_f32_e32 v54, v54, v68
	v_mul_f32_e32 v55, v55, v68
	ds_bpermute_b32 v80, v69, v74
	ds_bpermute_b32 v81, v69, v75
	ds_bpermute_b32 v78, v69, v76
	ds_bpermute_b32 v79, v69, v77
	global_load_dwordx4 v[68:71], v[64:65], off
	s_nop 0
	global_load_dwordx4 v[64:67], v[64:65], off offset:16
	v_mul_f32_e32 v62, v42, v62
	v_mul_f32_e32 v63, v43, v63
	v_mul_f32_e32 v60, v40, v60
	v_mul_f32_e32 v61, v41, v61
	v_mul_f32_e32 v58, v38, v58
	v_mul_f32_e32 v59, v39, v59
	v_mul_f32_e32 v56, v36, v56
	v_mul_f32_e32 v57, v37, v57
	v_mul_f32_e32 v54, v34, v54
	v_mul_f32_e32 v55, v35, v55
	v_mul_f32_e32 v52, v32, v52
	v_mul_f32_e32 v53, v33, v53
	s_waitcnt vmcnt(1)
	v_mov_b32_e32 v84, v69
	v_mov_b32_e32 v85, v71
	s_waitcnt lgkmcnt(2)
	v_mul_f32_e32 v80, v84, v80
	v_mul_f32_e32 v81, v85, v81
	s_waitcnt vmcnt(0)
	v_mov_b32_e32 v84, v65
	v_mov_b32_e32 v85, v67
	s_waitcnt lgkmcnt(0)
	v_mul_f32_e32 v78, v84, v78
	v_mul_f32_e32 v79, v85, v79
	v_xor_b32_e32 v69, 0x80000000, v80
	v_xor_b32_e32 v65, 0x80000000, v78
	v_xor_b32_e32 v67, 0x80000000, v79
	v_xor_b32_e32 v71, 0x80000000, v81
	v_cndmask_b32_e64 v81, v81, v71, s[4:5]
	v_cndmask_b32_e64 v80, v80, v69, s[4:5]
	v_cndmask_b32_e64 v79, v79, v67, s[4:5]
	v_cndmask_b32_e64 v78, v78, v65, s[4:5]
	v_mov_b32_e32 v65, v66
	v_mov_b32_e32 v69, v70
	v_fma_f32 v66, v64, v76, v78
	v_fma_f32 v67, v65, v77, v79
	v_fma_f32 v64, v68, v74, v80
	v_fma_f32 v65, v69, v75, v81

.LBB0_375:
	s_andn2_b64 vcc, exec, s[42:43]
	v_and_b32_e32 v66, 0x1fef, v56
	s_cbranch_vccnz .LBB0_377
	v_lshlrev_b32_e32 v52, 4, v66
	v_cndmask_b32_e64 v57, v230, v52, s[0:1]
	v_mul_f32_e32 v52, v50, v50
	v_mul_f32_e32 v53, v51, v51
	v_mul_f32_e32 v54, v48, v48
	v_mul_f32_e32 v55, v49, v49
	s_mov_b32 s0, 0x800000
	v_pk_mov_b32 v[58:59], v[54:55], v[52:53] op_sel:[1,0]
	v_mov_b32_e32 v55, v53
	v_add_f32_e32 v52, v58, v54
	v_add_f32_e32 v53, v59, v55
	v_mul_f32_e32 v54, v30, v30
	v_mul_f32_e32 v55, v31, v31
	v_mul_f32_e32 v58, v28, v28
	v_mul_f32_e32 v59, v29, v29
	v_add_f32_e32 v52, v52, v53
	v_mov_b32_e32 v53, v52
	v_pk_mov_b32 v[60:61], v[58:59], v[54:55] op_sel:[1,0]
	v_mov_b32_e32 v59, v55
	v_add_f32_e32 v54, v60, v58
	v_add_f32_e32 v55, v61, v59
	v_mul_f32_e32 v58, v20, v20
	v_mul_f32_e32 v59, v21, v21
	v_add_f32_e32 v54, v54, v55
	v_mov_b32_e32 v55, v54
	v_mov_b32_e32 v53, v58
	v_mov_b32_e32 v55, v59
	v_add_f32_e32 v52, v52, v54
	v_add_f32_e32 v53, v53, v55
	v_mul_f32_e32 v54, v25, v25
	v_mul_f32_e32 v58, v27, v27
	v_mul_f32_e32 v60, v22, v22
	v_mul_f32_e32 v61, v23, v23
	v_fma_f32 v55, v25, v25, v54
	v_fma_f32 v54, v24, v24, v54
	v_fma_f32 v59, v27, v27, v58
	v_fma_f32 v58, v26, v26, v58
	v_mov_b32_e32 v55, v60
	v_mov_b32_e32 v59, v61
	v_add_f32_e32 v54, v54, v58
	v_add_f32_e32 v55, v55, v59
	s_nop 0
	v_add_f32_e32 v52, v52, v54
	v_add_f32_e32 v53, v53, v55
	v_and_b32_e32 v54, 64, v229
	v_add_f32_e32 v52, v52, v53
	v_xor_b32_e32 v53, 16, v229
	v_add_u32_e32 v54, 64, v54
	v_cmp_lt_i32_e32 vcc, v53, v54
	s_nop 1
	v_cndmask_b32_e32 v53, v229, v53, vcc
	v_lshlrev_b32_e32 v53, 2, v53
	ds_bpermute_b32 v53, v53, v52
	s_waitcnt lgkmcnt(0)
	v_add_f32_e32 v52, v52, v53
	v_xor_b32_e32 v53, 32, v229
	v_cmp_lt_i32_e32 vcc, v53, v54
	s_nop 1
	v_cndmask_b32_e32 v53, v229, v53, vcc
	v_lshlrev_b32_e32 v53, 2, v53
	ds_bpermute_b32 v54, v53, v52
	s_waitcnt lgkmcnt(0)
	v_add_f32_e32 v52, v52, v54
	v_fmamk_f32 v52, v52, 0x3c800000, v226
	v_cmp_gt_f32_e32 vcc, s0, v52
	v_mul_f32_e32 v54, 0x4b800000, v52
	s_nop 0
	v_cndmask_b32_e32 v52, v52, v54, vcc
	v_rsq_f32_e32 v52, v52
	s_nop 0
	v_mul_f32_e32 v54, 0x45800000, v52
	v_cndmask_b32_e32 v52, v52, v54, vcc
	v_mul_f32_e32 v48, v48, v52
	v_mul_f32_e32 v49, v49, v52
	v_mul_f32_e32 v50, v50, v52
	v_mul_f32_e32 v51, v51, v52
	s_waitcnt vmcnt(0)
	v_mul_f32_e32 v58, v44, v48
	v_mul_f32_e32 v59, v45, v49
	v_lshlrev_b32_e32 v48, 2, v57
	v_mov_b32_e32 v49, v3
	v_mul_f32_e32 v60, v46, v50
	v_mul_f32_e32 v61, v47, v51
	v_lshl_add_u64 v[48:49], v[164:165], 0, v[48:49]
	v_mul_f32_e32 v28, v28, v52
	v_mul_f32_e32 v29, v29, v52
	v_mul_f32_e32 v30, v30, v52
	v_mul_f32_e32 v31, v31, v52
	v_mul_f32_e32 v24, v24, v52
	v_mul_f32_e32 v25, v25, v52
	v_mul_f32_e32 v26, v26, v52
	v_mul_f32_e32 v27, v27, v52
	v_mul_f32_e32 v20, v20, v52
	v_mul_f32_e32 v21, v21, v52
	v_mul_f32_e32 v22, v22, v52
	v_mul_f32_e32 v23, v23, v52
	ds_bpermute_b32 v64, v53, v58
	ds_bpermute_b32 v65, v53, v59
	ds_bpermute_b32 v62, v53, v60
	ds_bpermute_b32 v63, v53, v61
	global_load_dwordx4 v[52:55], v[48:49], off
	s_nop 0
	global_load_dwordx4 v[48:51], v[48:49], off offset:16
	v_mul_f32_e32 v30, v42, v30
	v_mul_f32_e32 v31, v43, v31
	v_mul_f32_e32 v28, v40, v28
	v_mul_f32_e32 v29, v41, v29
	v_mul_f32_e32 v26, v38, v26
	v_mul_f32_e32 v27, v39, v27
	v_mul_f32_e32 v24, v36, v24
	v_mul_f32_e32 v25, v37, v25
	v_mul_f32_e32 v22, v34, v22
	v_mul_f32_e32 v23, v35, v23
	v_mul_f32_e32 v20, v32, v20
	v_mul_f32_e32 v21, v33, v21
	s_waitcnt vmcnt(1)
	v_mov_b32_e32 v68, v53
	v_mov_b32_e32 v69, v55
	s_waitcnt lgkmcnt(2)
	v_mul_f32_e32 v64, v68, v64
	v_mul_f32_e32 v65, v69, v65
	s_waitcnt vmcnt(0)
	v_mov_b32_e32 v68, v49
	v_mov_b32_e32 v69, v51
	s_waitcnt lgkmcnt(0)
	v_mul_f32_e32 v62, v68, v62
	v_mul_f32_e32 v63, v69, v63
	v_xor_b32_e32 v53, 0x80000000, v64
	v_xor_b32_e32 v49, 0x80000000, v62
	v_xor_b32_e32 v51, 0x80000000, v63
	v_xor_b32_e32 v55, 0x80000000, v65
	v_cndmask_b32_e64 v65, v65, v55, s[4:5]
	v_cndmask_b32_e64 v64, v64, v53, s[4:5]
	v_cndmask_b32_e64 v63, v63, v51, s[4:5]
	v_cndmask_b32_e64 v62, v62, v49, s[4:5]
	v_mov_b32_e32 v49, v50
	v_mov_b32_e32 v53, v54
	v_fma_f32 v50, v48, v60, v62
	v_fma_f32 v51, v49, v61, v63
	v_fma_f32 v48, v52, v58, v64
	v_fma_f32 v49, v53, v59, v65

.LBB0_398:
	s_andn2_b64 vcc, exec, s[42:43]
	v_and_b32_e32 v48, 0x1fff, v24
	s_cbranch_vccnz .LBB0_400
	v_lshlrev_b32_e32 v20, 4, v48
	v_cndmask_b32_e64 v25, v230, v20, s[0:1]
	v_mul_f32_e32 v20, v18, v18
	v_mul_f32_e32 v21, v19, v19
	v_mul_f32_e32 v22, v16, v16
	v_mul_f32_e32 v23, v17, v17
	s_mov_b32 s0, 0x800000
	v_pk_mov_b32 v[26:27], v[22:23], v[20:21] op_sel:[1,0]
	v_mov_b32_e32 v23, v21
	v_add_f32_e32 v20, v26, v22
	v_add_f32_e32 v21, v27, v23
	v_mul_f32_e32 v22, v14, v14
	v_mul_f32_e32 v23, v15, v15
	v_mul_f32_e32 v26, v12, v12
	v_mul_f32_e32 v27, v13, v13
	v_add_f32_e32 v20, v20, v21
	v_mov_b32_e32 v21, v20
	v_pk_mov_b32 v[28:29], v[26:27], v[22:23] op_sel:[1,0]
	v_mov_b32_e32 v27, v23
	v_add_f32_e32 v22, v28, v26
	v_add_f32_e32 v23, v29, v27
	v_mul_f32_e32 v26, v4, v4
	v_mul_f32_e32 v27, v5, v5
	v_add_f32_e32 v22, v22, v23
	v_mov_b32_e32 v23, v22
	v_mov_b32_e32 v21, v26
	v_mov_b32_e32 v23, v27
	v_add_f32_e32 v20, v20, v22
	v_add_f32_e32 v21, v21, v23
	v_mul_f32_e32 v22, v9, v9
	v_mul_f32_e32 v26, v11, v11
	v_mul_f32_e32 v28, v6, v6
	v_mul_f32_e32 v29, v7, v7
	v_fma_f32 v23, v9, v9, v22
	v_fma_f32 v22, v8, v8, v22
	v_fma_f32 v27, v11, v11, v26
	v_fma_f32 v26, v10, v10, v26
	v_mov_b32_e32 v23, v28
	v_mov_b32_e32 v27, v29
	v_add_f32_e32 v22, v22, v26
	v_add_f32_e32 v23, v23, v27
	s_nop 0
	v_add_f32_e32 v20, v20, v22
	v_add_f32_e32 v21, v21, v23
	v_and_b32_e32 v22, 64, v229
	v_add_f32_e32 v20, v20, v21
	v_xor_b32_e32 v21, 16, v229
	v_add_u32_e32 v22, 64, v22
	v_cmp_lt_i32_e32 vcc, v21, v22
	s_nop 1
	v_cndmask_b32_e32 v21, v229, v21, vcc
	v_lshlrev_b32_e32 v21, 2, v21
	ds_bpermute_b32 v21, v21, v20
	s_waitcnt lgkmcnt(0)
	v_add_f32_e32 v20, v20, v21
	v_xor_b32_e32 v21, 32, v229
	v_cmp_lt_i32_e32 vcc, v21, v22
	s_nop 1
	v_cndmask_b32_e32 v21, v229, v21, vcc
	v_lshlrev_b32_e32 v21, 2, v21
	ds_bpermute_b32 v22, v21, v20
	s_waitcnt lgkmcnt(0)
	v_add_f32_e32 v20, v20, v22
	v_fmamk_f32 v20, v20, 0x3c800000, v226
	v_cmp_gt_f32_e32 vcc, s0, v20
	v_mul_f32_e32 v22, 0x4b800000, v20
	s_nop 0
	v_cndmask_b32_e32 v20, v20, v22, vcc
	v_rsq_f32_e32 v20, v20
	s_nop 0
	v_mul_f32_e32 v22, 0x45800000, v20
	v_cndmask_b32_e32 v20, v20, v22, vcc
	v_mul_f32_e32 v16, v16, v20
	v_mul_f32_e32 v17, v17, v20
	v_mul_f32_e32 v18, v18, v20
	v_mul_f32_e32 v19, v19, v20
	s_waitcnt vmcnt(0)
	v_mul_f32_e32 v26, v44, v16
	v_mul_f32_e32 v27, v45, v17
	v_lshlrev_b32_e32 v16, 2, v25
	v_mov_b32_e32 v17, v3
	v_mul_f32_e32 v28, v46, v18
	v_mul_f32_e32 v29, v47, v19
	v_mul_f32_e32 v4, v4, v20
	v_mul_f32_e32 v5, v5, v20
	v_lshl_add_u64 v[16:17], v[164:165], 0, v[16:17]
	v_mul_f32_e32 v12, v12, v20
	v_mul_f32_e32 v13, v13, v20
	v_mul_f32_e32 v14, v14, v20
	v_mul_f32_e32 v15, v15, v20
	v_mul_f32_e32 v8, v8, v20
	v_mul_f32_e32 v9, v9, v20
	v_mul_f32_e32 v10, v10, v20
	v_mul_f32_e32 v11, v11, v20
	v_mul_f32_e32 v6, v6, v20
	v_mul_f32_e32 v7, v7, v20
	v_mul_f32_e32 v4, v32, v4
	v_mul_f32_e32 v5, v33, v5
	ds_bpermute_b32 v32, v21, v26
	ds_bpermute_b32 v33, v21, v27
	ds_bpermute_b32 v30, v21, v28
	ds_bpermute_b32 v31, v21, v29
	global_load_dwordx4 v[20:23], v[16:17], off
	s_nop 0
	global_load_dwordx4 v[16:19], v[16:17], off offset:16
	v_mul_f32_e32 v6, v34, v6
	v_mul_f32_e32 v7, v35, v7
	v_mul_f32_e32 v14, v42, v14
	v_mul_f32_e32 v15, v43, v15
	v_mul_f32_e32 v12, v40, v12
	v_mul_f32_e32 v13, v41, v13
	v_mul_f32_e32 v10, v38, v10
	v_mul_f32_e32 v11, v39, v11
	v_mul_f32_e32 v8, v36, v8
	v_mul_f32_e32 v9, v37, v9
	s_waitcnt vmcnt(1)
	v_mov_b32_e32 v34, v21
	v_mov_b32_e32 v35, v23
	s_waitcnt lgkmcnt(2)
	v_mul_f32_e32 v32, v34, v32
	v_mul_f32_e32 v33, v35, v33
	s_waitcnt vmcnt(0)
	v_mov_b32_e32 v34, v17
	v_mov_b32_e32 v35, v19
	s_waitcnt lgkmcnt(0)
	v_mul_f32_e32 v30, v34, v30
	v_mul_f32_e32 v31, v35, v31
	v_xor_b32_e32 v21, 0x80000000, v32
	v_xor_b32_e32 v17, 0x80000000, v30
	v_xor_b32_e32 v19, 0x80000000, v31
	v_xor_b32_e32 v23, 0x80000000, v33
	v_cndmask_b32_e64 v33, v33, v23, s[4:5]
	v_cndmask_b32_e64 v32, v32, v21, s[4:5]
	v_cndmask_b32_e64 v31, v31, v19, s[4:5]
	v_cndmask_b32_e64 v30, v30, v17, s[4:5]
	v_mov_b32_e32 v17, v18
	v_mov_b32_e32 v21, v22
	v_fma_f32 v18, v16, v28, v30
	v_fma_f32 v19, v17, v29, v31
	v_fma_f32 v16, v20, v26, v32
	v_fma_f32 v17, v21, v27, v33

.LBB0_448:
	s_andn2_b64 vcc, exec, s[30:31]
	s_cbranch_vccnz .LBB0_450
	v_mul_f32_e32 v166, v146, v146
	v_mul_f32_e32 v167, v147, v147
	v_mul_f32_e32 v168, v144, v144
	v_mul_f32_e32 v169, v145, v145
	s_movk_i32 s11, 0x4000
	v_pk_mov_b32 v[170:171], v[168:169], v[166:167] op_sel:[1,0]
	v_mov_b32_e32 v169, v167
	v_add_f32_e32 v166, v170, v168
	v_add_f32_e32 v167, v171, v169
	v_mul_f32_e32 v168, v142, v142
	v_mul_f32_e32 v169, v143, v143
	v_mul_f32_e32 v170, v140, v140
	v_mul_f32_e32 v171, v141, v141
	v_lshlrev_b32_e32 v2, 4, v164
	v_pk_mov_b32 v[172:173], v[170:171], v[168:169] op_sel:[1,0]
	v_mov_b32_e32 v171, v169
	v_cmp_gt_i32_e32 vcc, s11, v164
	v_and_b32_e32 v2, 0x1fcf0, v2
	v_add_f32_e32 v168, v172, v170
	v_add_f32_e32 v169, v173, v171
	v_cndmask_b32_e32 v165, v230, v2, vcc
	v_mul_f32_e32 v2, v132, v132
	v_mul_f32_e32 v170, v133, v133
	v_add_f32_e32 v166, v166, v167
	v_mov_b32_e32 v167, v166
	v_add_f32_e32 v168, v168, v169
	v_mov_b32_e32 v169, v168
	v_mov_b32_e32 v167, v2
	v_mov_b32_e32 v169, v170
	v_mul_f32_e32 v2, v137, v137
	v_mul_f32_e32 v171, v134, v134
	v_add_f32_e32 v166, v166, v168
	v_add_f32_e32 v167, v167, v169
	v_fma_f32 v168, v136, v136, v2
	v_fma_f32 v169, v137, v137, v2
	v_mul_f32_e32 v2, v139, v139
	v_mul_f32_e32 v172, v135, v135
	v_mov_b32_e32 v169, v171
	v_fma_f32 v170, v138, v138, v2
	v_fma_f32 v171, v139, v139, v2
	s_mov_b32 s11, 0x800000
	v_mov_b32_e32 v171, v172
	v_add_f32_e32 v168, v168, v170
	v_add_f32_e32 v169, v169, v171
	s_mov_b32 s30, 0x3e38aa3b
	v_add_f32_e32 v166, v166, v168
	v_add_f32_e32 v167, v167, v169
	s_nop 0
	v_add_f32_e32 v2, v166, v167
	v_and_b32_e32 v167, 64, v229
	v_xor_b32_e32 v166, 16, v229
	v_add_u32_e32 v167, 64, v167
	v_cmp_lt_i32_e32 vcc, v166, v167
	s_nop 1
	v_cndmask_b32_e32 v166, v229, v166, vcc
	v_lshlrev_b32_e32 v166, 2, v166
	ds_bpermute_b32 v166, v166, v2
	s_waitcnt lgkmcnt(0)
	v_add_f32_e32 v2, v2, v166
	v_xor_b32_e32 v166, 32, v229
	v_cmp_lt_i32_e32 vcc, v166, v167
	s_nop 1
	v_cndmask_b32_e32 v166, v229, v166, vcc
	v_lshlrev_b32_e32 v177, 2, v166
	ds_bpermute_b32 v166, v177, v2
	s_waitcnt lgkmcnt(0)
	v_add_f32_e32 v2, v2, v166
	v_fmamk_f32 v2, v2, 0x3c800000, v226
	v_cmp_gt_f32_e32 vcc, s11, v2
	v_mul_f32_e32 v166, 0x4b800000, v2
	s_nop 0
	v_cndmask_b32_e32 v2, v2, v166, vcc
	v_rsq_f32_e32 v2, v2
	s_nop 0
	v_mul_f32_e32 v166, 0x45800000, v2
	v_cndmask_b32_e32 v2, v2, v166, vcc
	v_mul_f32_e32 v144, v144, v2
	v_mul_f32_e32 v145, v145, v2
	v_mul_f32_e32 v146, v146, v2
	v_mul_f32_e32 v147, v147, v2
	v_mul_f32_e32 v142, v142, v2
	v_mul_f32_e32 v143, v143, v2
	v_mul_f32_e32 v140, v140, v2
	v_mul_f32_e32 v141, v141, v2
	v_mul_f32_e32 v138, v138, v2
	v_mul_f32_e32 v139, v139, v2
	v_mul_f32_e32 v136, v136, v2
	v_mul_f32_e32 v137, v137, v2
	v_mul_f32_e32 v134, v134, v2
	v_mul_f32_e32 v135, v135, v2
	v_mul_f32_e32 v132, v132, v2
	v_mul_f32_e32 v133, v133, v2
	v_lshlrev_b32_e32 v2, 2, v165
	s_waitcnt vmcnt(0)
	v_mul_f32_e32 v172, v32, v144
	v_mul_f32_e32 v173, v33, v145
	v_mul_f32_e32 v144, v24, v136
	v_mul_f32_e32 v145, v25, v137
	v_lshl_add_u64 v[136:137], v[154:155], 0, v[2:3]
	v_mul_f32_e32 v170, v34, v146
	v_mul_f32_e32 v171, v35, v147
	v_mul_f32_e32 v166, v28, v140
	v_mul_f32_e32 v167, v29, v141
	v_mul_f32_e32 v168, v30, v142
	v_mul_f32_e32 v169, v31, v143
	v_mul_f32_e32 v146, v26, v138
	v_mul_f32_e32 v147, v27, v139
	v_mul_f32_e32 v140, v20, v132
	v_mul_f32_e32 v141, v21, v133
	v_mul_f32_e32 v142, v22, v134
	v_mul_f32_e32 v143, v23, v135
	global_load_dwordx4 v[132:135], v[136:137], off offset:16
	s_nop 0
	global_load_dwordx4 v[136:139], v[136:137], off
	ds_bpermute_b32 v174, v177, v172
	ds_bpermute_b32 v175, v177, v173
	ds_bpermute_b32 v176, v177, v170
	ds_bpermute_b32 v177, v177, v171
	v_ashrrev_i32_e32 v165, 31, v164
	s_waitcnt vmcnt(1)
	v_mov_b32_e32 v180, v133
	v_mov_b32_e32 v181, v135
	s_waitcnt lgkmcnt(0)
	v_mul_f32_e32 v176, v180, v176
	v_mul_f32_e32 v177, v181, v177
	s_waitcnt vmcnt(0)
	v_mov_b32_e32 v180, v137
	v_mov_b32_e32 v181, v139
	v_mul_f32_e32 v174, v180, v174
	v_mul_f32_e32 v175, v181, v175
	v_xor_b32_e32 v135, 0x80000000, v176
	v_xor_b32_e32 v2, 0x80000000, v174
	v_xor_b32_e32 v133, 0x80000000, v175
	v_xor_b32_e32 v137, 0x80000000, v177
	v_cndmask_b32_e64 v177, v177, v137, s[4:5]
	v_cndmask_b32_e64 v176, v176, v135, s[4:5]
	v_cndmask_b32_e64 v175, v175, v133, s[4:5]
	v_cndmask_b32_e64 v174, v174, v2, s[4:5]
	v_mov_b32_e32 v137, v138
	v_mov_b32_e32 v133, v134
	v_lshlrev_b64 v[134:135], 11, v[164:165]
	v_fma_f32 v136, v136, v172, v174
	v_fma_f32 v137, v137, v173, v175
	v_lshl_add_u64 v[134:135], s[8:9], 0, v[134:135]
	v_fma_f32 v132, v132, v170, v176
	v_fma_f32 v133, v133, v171, v177
	v_lshl_add_u64 v[134:135], s[24:25], 1, v[134:135]
	v_lshlrev_b32_e32 v2, 1, v152
	v_mul_f32_e32 v136, s30, v136
	v_mul_f32_e32 v137, s30, v137
	v_lshl_add_u64 v[134:135], v[134:135], 0, v[2:3]
	v_mul_f32_e32 v132, s30, v132
	v_mul_f32_e32 v133, s30, v133
	v_cvt_pk_bf16_f32 v136, v136, v137
	s_nop 0
	v_cvt_pk_bf16_f32 v137, v132, v133
	global_store_dwordx2 v[134:135], v[136:137], off
	v_mul_f32_e32 v136, s30, v166
	v_mul_f32_e32 v137, s30, v167
	v_mul_f32_e32 v132, s30, v168
	v_mul_f32_e32 v133, s30, v169
	v_cvt_pk_bf16_f32 v136, v136, v137
	s_nop 0
	v_cvt_pk_bf16_f32 v137, v132, v133
	global_store_dwordx2 v[134:135], v[136:137], off offset:32
	v_mul_f32_e32 v136, s30, v144
	v_mul_f32_e32 v137, s30, v145
	v_mul_f32_e32 v132, s30, v146
	v_mul_f32_e32 v133, s30, v147
	v_cvt_pk_bf16_f32 v136, v136, v137
	s_nop 0
	v_cvt_pk_bf16_f32 v137, v132, v133
	global_store_dwordx2 v[134:135], v[136:137], off offset:64
	v_mul_f32_e32 v136, s30, v140
	v_mul_f32_e32 v137, s30, v141
	v_mul_f32_e32 v132, s30, v142
	v_mul_f32_e32 v133, s30, v143
	v_cvt_pk_bf16_f32 v136, v136, v137
	s_nop 0
	v_cvt_pk_bf16_f32 v137, v132, v133
	global_store_dwordx2 v[134:135], v[136:137], off offset:96

.LBB0_456:
	s_andn2_b64 vcc, exec, s[30:31]
	s_cbranch_vccnz .LBB0_458
	v_mul_f32_e32 v134, v130, v130
	v_mul_f32_e32 v135, v131, v131
	v_mul_f32_e32 v136, v128, v128
	v_mul_f32_e32 v137, v129, v129
	s_movk_i32 s11, 0x4000
	v_pk_mov_b32 v[138:139], v[136:137], v[134:135] op_sel:[1,0]
	v_mov_b32_e32 v137, v135
	v_add_f32_e32 v134, v138, v136
	v_add_f32_e32 v135, v139, v137
	v_mul_f32_e32 v136, v126, v126
	v_mul_f32_e32 v137, v127, v127
	v_mul_f32_e32 v138, v124, v124
	v_mul_f32_e32 v139, v125, v125
	v_lshlrev_b32_e32 v2, 4, v132
	v_pk_mov_b32 v[140:141], v[138:139], v[136:137] op_sel:[1,0]
	v_mov_b32_e32 v139, v137
	v_cmp_gt_i32_e32 vcc, s11, v132
	v_and_b32_e32 v2, 0x1fdf0, v2
	v_add_f32_e32 v136, v140, v138
	v_add_f32_e32 v137, v141, v139
	v_cndmask_b32_e32 v133, v230, v2, vcc
	v_mul_f32_e32 v2, v116, v116
	v_mul_f32_e32 v138, v117, v117
	v_add_f32_e32 v134, v134, v135
	v_mov_b32_e32 v135, v134
	v_add_f32_e32 v136, v136, v137
	v_mov_b32_e32 v137, v136
	v_mov_b32_e32 v135, v2
	v_mov_b32_e32 v137, v138
	v_mul_f32_e32 v2, v121, v121
	v_mul_f32_e32 v139, v118, v118
	v_add_f32_e32 v134, v134, v136
	v_add_f32_e32 v135, v135, v137
	v_fma_f32 v136, v120, v120, v2
	v_fma_f32 v137, v121, v121, v2
	v_mul_f32_e32 v2, v123, v123
	v_mul_f32_e32 v140, v119, v119
	v_mov_b32_e32 v137, v139
	v_fma_f32 v138, v122, v122, v2
	v_fma_f32 v139, v123, v123, v2
	s_mov_b32 s11, 0x800000
	v_mov_b32_e32 v139, v140
	v_add_f32_e32 v136, v136, v138
	v_add_f32_e32 v137, v137, v139
	s_mov_b32 s30, 0x3e38aa3b
	v_add_f32_e32 v134, v134, v136
	v_add_f32_e32 v135, v135, v137
	s_nop 0
	v_add_f32_e32 v2, v134, v135
	v_and_b32_e32 v135, 64, v229
	v_xor_b32_e32 v134, 16, v229
	v_add_u32_e32 v135, 64, v135
	v_cmp_lt_i32_e32 vcc, v134, v135
	s_nop 1
	v_cndmask_b32_e32 v134, v229, v134, vcc
	v_lshlrev_b32_e32 v134, 2, v134
	ds_bpermute_b32 v134, v134, v2
	s_waitcnt lgkmcnt(0)
	v_add_f32_e32 v2, v2, v134
	v_xor_b32_e32 v134, 32, v229
	v_cmp_lt_i32_e32 vcc, v134, v135
	s_nop 1
	v_cndmask_b32_e32 v134, v229, v134, vcc
	v_lshlrev_b32_e32 v145, 2, v134
	ds_bpermute_b32 v134, v145, v2
	s_waitcnt lgkmcnt(0)
	v_add_f32_e32 v2, v2, v134
	v_fmamk_f32 v2, v2, 0x3c800000, v226
	v_cmp_gt_f32_e32 vcc, s11, v2
	v_mul_f32_e32 v134, 0x4b800000, v2
	s_nop 0
	v_cndmask_b32_e32 v2, v2, v134, vcc
	v_rsq_f32_e32 v2, v2
	s_nop 0
	v_mul_f32_e32 v134, 0x45800000, v2
	v_cndmask_b32_e32 v2, v2, v134, vcc
	v_mul_f32_e32 v128, v128, v2
	v_mul_f32_e32 v129, v129, v2
	v_mul_f32_e32 v130, v130, v2
	v_mul_f32_e32 v131, v131, v2
	v_mul_f32_e32 v126, v126, v2
	v_mul_f32_e32 v127, v127, v2
	v_mul_f32_e32 v124, v124, v2
	v_mul_f32_e32 v125, v125, v2
	v_mul_f32_e32 v122, v122, v2
	v_mul_f32_e32 v123, v123, v2
	v_mul_f32_e32 v120, v120, v2
	v_mul_f32_e32 v121, v121, v2
	v_mul_f32_e32 v118, v118, v2
	v_mul_f32_e32 v119, v119, v2
	v_mul_f32_e32 v116, v116, v2
	v_mul_f32_e32 v117, v117, v2
	v_lshlrev_b32_e32 v2, 2, v133
	s_waitcnt vmcnt(0)
	v_mul_f32_e32 v140, v32, v128
	v_mul_f32_e32 v141, v33, v129
	v_mul_f32_e32 v128, v24, v120
	v_mul_f32_e32 v129, v25, v121
	v_lshl_add_u64 v[120:121], v[154:155], 0, v[2:3]
	v_mul_f32_e32 v138, v34, v130
	v_mul_f32_e32 v139, v35, v131
	v_mul_f32_e32 v134, v28, v124
	v_mul_f32_e32 v135, v29, v125
	v_mul_f32_e32 v136, v30, v126
	v_mul_f32_e32 v137, v31, v127
	v_mul_f32_e32 v130, v26, v122
	v_mul_f32_e32 v131, v27, v123
	v_mul_f32_e32 v124, v20, v116
	v_mul_f32_e32 v125, v21, v117
	v_mul_f32_e32 v126, v22, v118
	v_mul_f32_e32 v127, v23, v119
	global_load_dwordx4 v[116:119], v[120:121], off offset:16
	s_nop 0
	global_load_dwordx4 v[120:123], v[120:121], off
	ds_bpermute_b32 v142, v145, v140
	ds_bpermute_b32 v143, v145, v141
	ds_bpermute_b32 v144, v145, v138
	ds_bpermute_b32 v145, v145, v139
	v_ashrrev_i32_e32 v133, 31, v132
	s_waitcnt vmcnt(1)
	v_mov_b32_e32 v146, v117
	v_mov_b32_e32 v147, v119
	s_waitcnt lgkmcnt(0)
	v_mul_f32_e32 v144, v146, v144
	v_mul_f32_e32 v145, v147, v145
	s_waitcnt vmcnt(0)
	v_mov_b32_e32 v146, v121
	v_mov_b32_e32 v147, v123
	v_mul_f32_e32 v142, v146, v142
	v_mul_f32_e32 v143, v147, v143
	v_xor_b32_e32 v119, 0x80000000, v144
	v_xor_b32_e32 v2, 0x80000000, v142
	v_xor_b32_e32 v117, 0x80000000, v143
	v_xor_b32_e32 v121, 0x80000000, v145
	v_cndmask_b32_e64 v145, v145, v121, s[4:5]
	v_cndmask_b32_e64 v144, v144, v119, s[4:5]
	v_cndmask_b32_e64 v143, v143, v117, s[4:5]
	v_cndmask_b32_e64 v142, v142, v2, s[4:5]
	v_mov_b32_e32 v121, v122
	v_mov_b32_e32 v117, v118
	v_lshlrev_b64 v[118:119], 11, v[132:133]
	v_fma_f32 v120, v120, v140, v142
	v_fma_f32 v121, v121, v141, v143
	v_lshl_add_u64 v[118:119], s[8:9], 0, v[118:119]
	v_fma_f32 v116, v116, v138, v144
	v_fma_f32 v117, v117, v139, v145
	v_lshl_add_u64 v[118:119], s[24:25], 1, v[118:119]
	v_lshlrev_b32_e32 v2, 1, v152
	v_mul_f32_e32 v120, s30, v120
	v_mul_f32_e32 v121, s30, v121
	v_lshl_add_u64 v[118:119], v[118:119], 0, v[2:3]
	v_mul_f32_e32 v116, s30, v116
	v_mul_f32_e32 v117, s30, v117
	v_cvt_pk_bf16_f32 v120, v120, v121
	s_nop 0
	v_cvt_pk_bf16_f32 v121, v116, v117
	global_store_dwordx2 v[118:119], v[120:121], off
	v_mul_f32_e32 v120, s30, v134
	v_mul_f32_e32 v121, s30, v135
	v_mul_f32_e32 v116, s30, v136
	v_mul_f32_e32 v117, s30, v137
	v_cvt_pk_bf16_f32 v120, v120, v121
	s_nop 0
	v_cvt_pk_bf16_f32 v121, v116, v117
	global_store_dwordx2 v[118:119], v[120:121], off offset:32
	v_mul_f32_e32 v120, s30, v128
	v_mul_f32_e32 v121, s30, v129
	v_mul_f32_e32 v116, s30, v130
	v_mul_f32_e32 v117, s30, v131
	v_cvt_pk_bf16_f32 v120, v120, v121
	s_nop 0
	v_cvt_pk_bf16_f32 v121, v116, v117
	global_store_dwordx2 v[118:119], v[120:121], off offset:64
	v_mul_f32_e32 v120, s30, v124
	v_mul_f32_e32 v121, s30, v125
	v_mul_f32_e32 v116, s30, v126
	v_mul_f32_e32 v117, s30, v127
	v_cvt_pk_bf16_f32 v120, v120, v121
	s_nop 0
	v_cvt_pk_bf16_f32 v121, v116, v117
	global_store_dwordx2 v[118:119], v[120:121], off offset:96

.LBB0_464:
	s_andn2_b64 vcc, exec, s[30:31]
	s_cbranch_vccnz .LBB0_466
	v_mul_f32_e32 v118, v114, v114
	v_mul_f32_e32 v119, v115, v115
	v_mul_f32_e32 v120, v112, v112
	v_mul_f32_e32 v121, v113, v113
	s_movk_i32 s11, 0x4000
	v_pk_mov_b32 v[122:123], v[120:121], v[118:119] op_sel:[1,0]
	v_mov_b32_e32 v121, v119
	v_add_f32_e32 v118, v122, v120
	v_add_f32_e32 v119, v123, v121
	v_mul_f32_e32 v120, v110, v110
	v_mul_f32_e32 v121, v111, v111
	v_mul_f32_e32 v122, v108, v108
	v_mul_f32_e32 v123, v109, v109
	v_lshlrev_b32_e32 v2, 4, v116
	v_pk_mov_b32 v[124:125], v[122:123], v[120:121] op_sel:[1,0]
	v_mov_b32_e32 v123, v121
	v_cmp_gt_i32_e32 vcc, s11, v116
	v_and_b32_e32 v2, 0x1fef0, v2
	v_add_f32_e32 v120, v124, v122
	v_add_f32_e32 v121, v125, v123
	v_cndmask_b32_e32 v117, v230, v2, vcc
	v_mul_f32_e32 v2, v100, v100
	v_mul_f32_e32 v122, v101, v101
	v_add_f32_e32 v118, v118, v119
	v_mov_b32_e32 v119, v118
	v_add_f32_e32 v120, v120, v121
	v_mov_b32_e32 v121, v120
	v_mov_b32_e32 v119, v2
	v_mov_b32_e32 v121, v122
	v_mul_f32_e32 v2, v105, v105
	v_mul_f32_e32 v123, v102, v102
	v_add_f32_e32 v118, v118, v120
	v_add_f32_e32 v119, v119, v121
	v_fma_f32 v120, v104, v104, v2
	v_fma_f32 v121, v105, v105, v2
	v_mul_f32_e32 v2, v107, v107
	v_mul_f32_e32 v124, v103, v103
	v_mov_b32_e32 v121, v123
	v_fma_f32 v122, v106, v106, v2
	v_fma_f32 v123, v107, v107, v2
	s_mov_b32 s11, 0x800000
	v_mov_b32_e32 v123, v124
	v_add_f32_e32 v120, v120, v122
	v_add_f32_e32 v121, v121, v123
	s_mov_b32 s30, 0x3e38aa3b
	v_add_f32_e32 v118, v118, v120
	v_add_f32_e32 v119, v119, v121
	s_nop 0
	v_add_f32_e32 v2, v118, v119
	v_and_b32_e32 v119, 64, v229
	v_xor_b32_e32 v118, 16, v229
	v_add_u32_e32 v119, 64, v119
	v_cmp_lt_i32_e32 vcc, v118, v119
	s_nop 1
	v_cndmask_b32_e32 v118, v229, v118, vcc
	v_lshlrev_b32_e32 v118, 2, v118
	ds_bpermute_b32 v118, v118, v2
	s_waitcnt lgkmcnt(0)
	v_add_f32_e32 v2, v2, v118
	v_xor_b32_e32 v118, 32, v229
	v_cmp_lt_i32_e32 vcc, v118, v119
	s_nop 1
	v_cndmask_b32_e32 v118, v229, v118, vcc
	v_lshlrev_b32_e32 v129, 2, v118
	ds_bpermute_b32 v118, v129, v2
	s_waitcnt lgkmcnt(0)
	v_add_f32_e32 v2, v2, v118
	v_fmamk_f32 v2, v2, 0x3c800000, v226
	v_cmp_gt_f32_e32 vcc, s11, v2
	v_mul_f32_e32 v118, 0x4b800000, v2
	s_nop 0
	v_cndmask_b32_e32 v2, v2, v118, vcc
	v_rsq_f32_e32 v2, v2
	s_nop 0
	v_mul_f32_e32 v118, 0x45800000, v2
	v_cndmask_b32_e32 v2, v2, v118, vcc
	v_mul_f32_e32 v112, v112, v2
	v_mul_f32_e32 v113, v113, v2
	v_mul_f32_e32 v114, v114, v2
	v_mul_f32_e32 v115, v115, v2
	v_mul_f32_e32 v110, v110, v2
	v_mul_f32_e32 v111, v111, v2
	v_mul_f32_e32 v108, v108, v2
	v_mul_f32_e32 v109, v109, v2
	v_mul_f32_e32 v106, v106, v2
	v_mul_f32_e32 v107, v107, v2
	v_mul_f32_e32 v104, v104, v2
	v_mul_f32_e32 v105, v105, v2
	v_mul_f32_e32 v102, v102, v2
	v_mul_f32_e32 v103, v103, v2
	v_mul_f32_e32 v100, v100, v2
	v_mul_f32_e32 v101, v101, v2
	v_lshlrev_b32_e32 v2, 2, v117
	s_waitcnt vmcnt(0)
	v_mul_f32_e32 v124, v32, v112
	v_mul_f32_e32 v125, v33, v113
	v_mul_f32_e32 v112, v24, v104
	v_mul_f32_e32 v113, v25, v105
	v_lshl_add_u64 v[104:105], v[154:155], 0, v[2:3]
	v_mul_f32_e32 v122, v34, v114
	v_mul_f32_e32 v123, v35, v115
	v_mul_f32_e32 v118, v28, v108
	v_mul_f32_e32 v119, v29, v109
	v_mul_f32_e32 v120, v30, v110
	v_mul_f32_e32 v121, v31, v111
	v_mul_f32_e32 v114, v26, v106
	v_mul_f32_e32 v115, v27, v107
	v_mul_f32_e32 v108, v20, v100
	v_mul_f32_e32 v109, v21, v101
	v_mul_f32_e32 v110, v22, v102
	v_mul_f32_e32 v111, v23, v103
	global_load_dwordx4 v[100:103], v[104:105], off offset:16
	s_nop 0
	global_load_dwordx4 v[104:107], v[104:105], off
	ds_bpermute_b32 v126, v129, v124
	ds_bpermute_b32 v127, v129, v125
	ds_bpermute_b32 v128, v129, v122
	ds_bpermute_b32 v129, v129, v123
	v_ashrrev_i32_e32 v117, 31, v116
	s_waitcnt vmcnt(1)
	v_mov_b32_e32 v130, v101
	v_mov_b32_e32 v131, v103
	s_waitcnt lgkmcnt(0)
	v_mul_f32_e32 v128, v130, v128
	v_mul_f32_e32 v129, v131, v129
	s_waitcnt vmcnt(0)
	v_mov_b32_e32 v130, v105
	v_mov_b32_e32 v131, v107
	v_mul_f32_e32 v126, v130, v126
	v_mul_f32_e32 v127, v131, v127
	v_xor_b32_e32 v103, 0x80000000, v128
	v_xor_b32_e32 v2, 0x80000000, v126
	v_xor_b32_e32 v101, 0x80000000, v127
	v_xor_b32_e32 v105, 0x80000000, v129
	v_cndmask_b32_e64 v129, v129, v105, s[4:5]
	v_cndmask_b32_e64 v128, v128, v103, s[4:5]
	v_cndmask_b32_e64 v127, v127, v101, s[4:5]
	v_cndmask_b32_e64 v126, v126, v2, s[4:5]
	v_mov_b32_e32 v105, v106
	v_mov_b32_e32 v101, v102
	v_lshlrev_b64 v[102:103], 11, v[116:117]
	v_fma_f32 v104, v104, v124, v126
	v_fma_f32 v105, v105, v125, v127
	v_lshl_add_u64 v[102:103], s[8:9], 0, v[102:103]
	v_fma_f32 v100, v100, v122, v128
	v_fma_f32 v101, v101, v123, v129
	v_lshl_add_u64 v[102:103], s[24:25], 1, v[102:103]
	v_lshlrev_b32_e32 v2, 1, v152
	v_mul_f32_e32 v104, s30, v104
	v_mul_f32_e32 v105, s30, v105
	v_lshl_add_u64 v[102:103], v[102:103], 0, v[2:3]
	v_mul_f32_e32 v100, s30, v100
	v_mul_f32_e32 v101, s30, v101
	v_cvt_pk_bf16_f32 v104, v104, v105
	s_nop 0
	v_cvt_pk_bf16_f32 v105, v100, v101
	global_store_dwordx2 v[102:103], v[104:105], off
	v_mul_f32_e32 v104, s30, v118
	v_mul_f32_e32 v105, s30, v119
	v_mul_f32_e32 v100, s30, v120
	v_mul_f32_e32 v101, s30, v121
	v_cvt_pk_bf16_f32 v104, v104, v105
	s_nop 0
	v_cvt_pk_bf16_f32 v105, v100, v101
	global_store_dwordx2 v[102:103], v[104:105], off offset:32
	v_mul_f32_e32 v104, s30, v112
	v_mul_f32_e32 v105, s30, v113
	v_mul_f32_e32 v100, s30, v114
	v_mul_f32_e32 v101, s30, v115
	v_cvt_pk_bf16_f32 v104, v104, v105
	s_nop 0
	v_cvt_pk_bf16_f32 v105, v100, v101
	global_store_dwordx2 v[102:103], v[104:105], off offset:64
	v_mul_f32_e32 v104, s30, v108
	v_mul_f32_e32 v105, s30, v109
	v_mul_f32_e32 v100, s30, v110
	v_mul_f32_e32 v101, s30, v111
	v_cvt_pk_bf16_f32 v104, v104, v105
	s_nop 0
	v_cvt_pk_bf16_f32 v105, v100, v101
	global_store_dwordx2 v[102:103], v[104:105], off offset:96

.LBB0_472:
	s_andn2_b64 vcc, exec, s[30:31]
	s_cbranch_vccnz .LBB0_474
	v_mul_f32_e32 v102, v98, v98
	v_mul_f32_e32 v103, v99, v99
	v_mul_f32_e32 v104, v96, v96
	v_mul_f32_e32 v105, v97, v97
	s_movk_i32 s11, 0x4000
	v_pk_mov_b32 v[106:107], v[104:105], v[102:103] op_sel:[1,0]
	v_mov_b32_e32 v105, v103
	v_add_f32_e32 v102, v106, v104
	v_add_f32_e32 v103, v107, v105
	v_mul_f32_e32 v104, v94, v94
	v_mul_f32_e32 v105, v95, v95
	v_mul_f32_e32 v106, v92, v92
	v_mul_f32_e32 v107, v93, v93
	v_lshlrev_b32_e32 v2, 4, v100
	v_pk_mov_b32 v[108:109], v[106:107], v[104:105] op_sel:[1,0]
	v_mov_b32_e32 v107, v105
	v_cmp_gt_i32_e32 vcc, s11, v100
	v_and_b32_e32 v2, 0x1fff0, v2
	v_add_f32_e32 v104, v108, v106
	v_add_f32_e32 v105, v109, v107
	v_cndmask_b32_e32 v101, v230, v2, vcc
	v_mul_f32_e32 v2, v84, v84
	v_mul_f32_e32 v106, v85, v85
	v_add_f32_e32 v102, v102, v103
	v_mov_b32_e32 v103, v102
	v_add_f32_e32 v104, v104, v105
	v_mov_b32_e32 v105, v104
	v_mov_b32_e32 v103, v2
	v_mov_b32_e32 v105, v106
	v_mul_f32_e32 v2, v89, v89
	v_mul_f32_e32 v107, v86, v86
	v_add_f32_e32 v102, v102, v104
	v_add_f32_e32 v103, v103, v105
	v_fma_f32 v104, v88, v88, v2
	v_fma_f32 v105, v89, v89, v2
	v_mul_f32_e32 v2, v91, v91
	v_mul_f32_e32 v108, v87, v87
	v_mov_b32_e32 v105, v107
	v_fma_f32 v106, v90, v90, v2
	v_fma_f32 v107, v91, v91, v2
	s_mov_b32 s11, 0x800000
	v_mov_b32_e32 v107, v108
	v_add_f32_e32 v104, v104, v106
	v_add_f32_e32 v105, v105, v107
	s_mov_b32 s30, 0x3e38aa3b
	v_add_f32_e32 v102, v102, v104
	v_add_f32_e32 v103, v103, v105
	s_nop 0
	v_add_f32_e32 v2, v102, v103
	v_and_b32_e32 v103, 64, v229
	v_xor_b32_e32 v102, 16, v229
	v_add_u32_e32 v103, 64, v103
	v_cmp_lt_i32_e32 vcc, v102, v103
	s_nop 1
	v_cndmask_b32_e32 v102, v229, v102, vcc
	v_lshlrev_b32_e32 v102, 2, v102
	ds_bpermute_b32 v102, v102, v2
	s_waitcnt lgkmcnt(0)
	v_add_f32_e32 v2, v2, v102
	v_xor_b32_e32 v102, 32, v229
	v_cmp_lt_i32_e32 vcc, v102, v103
	s_nop 1
	v_cndmask_b32_e32 v102, v229, v102, vcc
	v_lshlrev_b32_e32 v113, 2, v102
	ds_bpermute_b32 v102, v113, v2
	s_waitcnt lgkmcnt(0)
	v_add_f32_e32 v2, v2, v102
	v_fmamk_f32 v2, v2, 0x3c800000, v226
	v_cmp_gt_f32_e32 vcc, s11, v2
	v_mul_f32_e32 v102, 0x4b800000, v2
	s_nop 0
	v_cndmask_b32_e32 v2, v2, v102, vcc
	v_rsq_f32_e32 v2, v2
	s_nop 0
	v_mul_f32_e32 v102, 0x45800000, v2
	v_cndmask_b32_e32 v2, v2, v102, vcc
	v_mul_f32_e32 v96, v96, v2
	v_mul_f32_e32 v97, v97, v2
	v_mul_f32_e32 v98, v98, v2
	v_mul_f32_e32 v99, v99, v2
	v_mul_f32_e32 v94, v94, v2
	v_mul_f32_e32 v95, v95, v2
	v_mul_f32_e32 v92, v92, v2
	v_mul_f32_e32 v93, v93, v2
	v_mul_f32_e32 v90, v90, v2
	v_mul_f32_e32 v91, v91, v2
	v_mul_f32_e32 v88, v88, v2
	v_mul_f32_e32 v89, v89, v2
	v_mul_f32_e32 v86, v86, v2
	v_mul_f32_e32 v87, v87, v2
	v_mul_f32_e32 v84, v84, v2
	v_mul_f32_e32 v85, v85, v2
	v_lshlrev_b32_e32 v2, 2, v101
	s_waitcnt vmcnt(0)
	v_mul_f32_e32 v108, v32, v96
	v_mul_f32_e32 v109, v33, v97
	v_mul_f32_e32 v96, v24, v88
	v_mul_f32_e32 v97, v25, v89
	v_lshl_add_u64 v[88:89], v[154:155], 0, v[2:3]
	v_mul_f32_e32 v106, v34, v98
	v_mul_f32_e32 v107, v35, v99
	v_mul_f32_e32 v102, v28, v92
	v_mul_f32_e32 v103, v29, v93
	v_mul_f32_e32 v104, v30, v94
	v_mul_f32_e32 v105, v31, v95
	v_mul_f32_e32 v98, v26, v90
	v_mul_f32_e32 v99, v27, v91
	v_mul_f32_e32 v92, v20, v84
	v_mul_f32_e32 v93, v21, v85
	v_mul_f32_e32 v94, v22, v86
	v_mul_f32_e32 v95, v23, v87
	global_load_dwordx4 v[84:87], v[88:89], off offset:16
	s_nop 0
	global_load_dwordx4 v[88:91], v[88:89], off
	ds_bpermute_b32 v110, v113, v108
	ds_bpermute_b32 v111, v113, v109
	ds_bpermute_b32 v112, v113, v106
	ds_bpermute_b32 v113, v113, v107
	v_ashrrev_i32_e32 v101, 31, v100
	s_waitcnt vmcnt(1)
	v_mov_b32_e32 v114, v85
	v_mov_b32_e32 v115, v87
	s_waitcnt lgkmcnt(0)
	v_mul_f32_e32 v112, v114, v112
	v_mul_f32_e32 v113, v115, v113
	s_waitcnt vmcnt(0)
	v_mov_b32_e32 v114, v89
	v_mov_b32_e32 v115, v91
	v_mul_f32_e32 v110, v114, v110
	v_mul_f32_e32 v111, v115, v111
	v_xor_b32_e32 v87, 0x80000000, v112
	v_xor_b32_e32 v2, 0x80000000, v110
	v_xor_b32_e32 v85, 0x80000000, v111
	v_xor_b32_e32 v89, 0x80000000, v113
	v_cndmask_b32_e64 v113, v113, v89, s[4:5]
	v_cndmask_b32_e64 v112, v112, v87, s[4:5]
	v_cndmask_b32_e64 v111, v111, v85, s[4:5]
	v_cndmask_b32_e64 v110, v110, v2, s[4:5]
	v_mov_b32_e32 v89, v90
	v_mov_b32_e32 v85, v86
	v_lshlrev_b64 v[86:87], 11, v[100:101]
	v_fma_f32 v88, v88, v108, v110
	v_fma_f32 v89, v89, v109, v111
	v_lshl_add_u64 v[86:87], s[8:9], 0, v[86:87]
	v_fma_f32 v84, v84, v106, v112
	v_fma_f32 v85, v85, v107, v113
	v_lshl_add_u64 v[86:87], s[24:25], 1, v[86:87]
	v_lshlrev_b32_e32 v2, 1, v152
	v_mul_f32_e32 v88, s30, v88
	v_mul_f32_e32 v89, s30, v89
	v_lshl_add_u64 v[86:87], v[86:87], 0, v[2:3]
	v_mul_f32_e32 v84, s30, v84
	v_mul_f32_e32 v85, s30, v85
	v_cvt_pk_bf16_f32 v88, v88, v89
	s_nop 0
	v_cvt_pk_bf16_f32 v89, v84, v85
	global_store_dwordx2 v[86:87], v[88:89], off
	v_mul_f32_e32 v88, s30, v102
	v_mul_f32_e32 v89, s30, v103
	v_mul_f32_e32 v84, s30, v104
	v_mul_f32_e32 v85, s30, v105
	v_cvt_pk_bf16_f32 v88, v88, v89
	s_nop 0
	v_cvt_pk_bf16_f32 v89, v84, v85
	global_store_dwordx2 v[86:87], v[88:89], off offset:32
	v_mul_f32_e32 v88, s30, v96
	v_mul_f32_e32 v89, s30, v97
	v_mul_f32_e32 v84, s30, v98
	v_mul_f32_e32 v85, s30, v99
	v_cvt_pk_bf16_f32 v88, v88, v89
	s_nop 0
	v_cvt_pk_bf16_f32 v89, v84, v85
	global_store_dwordx2 v[86:87], v[88:89], off offset:64
	v_mul_f32_e32 v88, s30, v92
	v_mul_f32_e32 v89, s30, v93
	v_mul_f32_e32 v84, s30, v94
	v_mul_f32_e32 v85, s30, v95
	v_cvt_pk_bf16_f32 v88, v88, v89
	s_nop 0
	v_cvt_pk_bf16_f32 v89, v84, v85
	global_store_dwordx2 v[86:87], v[88:89], off offset:96

.LBB0_480:
	s_andn2_b64 vcc, exec, s[30:31]
	s_cbranch_vccnz .LBB0_482
	v_mul_f32_e32 v86, v82, v82
	v_mul_f32_e32 v87, v83, v83
	v_mul_f32_e32 v88, v80, v80
	v_mul_f32_e32 v89, v81, v81
	s_movk_i32 s11, 0x4000
	v_pk_mov_b32 v[90:91], v[88:89], v[86:87] op_sel:[1,0]
	v_mov_b32_e32 v89, v87
	v_add_f32_e32 v86, v90, v88
	v_add_f32_e32 v87, v91, v89
	v_mul_f32_e32 v88, v78, v78
	v_mul_f32_e32 v89, v79, v79
	v_mul_f32_e32 v90, v76, v76
	v_mul_f32_e32 v91, v77, v77
	v_lshlrev_b32_e32 v2, 4, v84
	v_pk_mov_b32 v[92:93], v[90:91], v[88:89] op_sel:[1,0]
	v_mov_b32_e32 v91, v89
	v_cmp_gt_i32_e32 vcc, s11, v84
	v_and_b32_e32 v2, 0x1fcf0, v2
	v_add_f32_e32 v88, v92, v90
	v_add_f32_e32 v89, v93, v91
	v_cndmask_b32_e32 v85, v230, v2, vcc
	v_mul_f32_e32 v2, v68, v68
	v_mul_f32_e32 v90, v69, v69
	v_add_f32_e32 v86, v86, v87
	v_mov_b32_e32 v87, v86
	v_add_f32_e32 v88, v88, v89
	v_mov_b32_e32 v89, v88
	v_mov_b32_e32 v87, v2
	v_mov_b32_e32 v89, v90
	v_mul_f32_e32 v2, v73, v73
	v_mul_f32_e32 v91, v70, v70
	v_add_f32_e32 v86, v86, v88
	v_add_f32_e32 v87, v87, v89
	v_fma_f32 v88, v72, v72, v2
	v_fma_f32 v89, v73, v73, v2
	v_mul_f32_e32 v2, v75, v75
	v_mul_f32_e32 v92, v71, v71
	v_mov_b32_e32 v89, v91
	v_fma_f32 v90, v74, v74, v2
	v_fma_f32 v91, v75, v75, v2
	s_mov_b32 s11, 0x800000
	v_mov_b32_e32 v91, v92
	v_add_f32_e32 v88, v88, v90
	v_add_f32_e32 v89, v89, v91
	s_mov_b32 s30, 0x3e38aa3b
	v_add_f32_e32 v86, v86, v88
	v_add_f32_e32 v87, v87, v89
	s_nop 0
	v_add_f32_e32 v2, v86, v87
	v_and_b32_e32 v87, 64, v229
	v_xor_b32_e32 v86, 16, v229
	v_add_u32_e32 v87, 64, v87
	v_cmp_lt_i32_e32 vcc, v86, v87
	s_nop 1
	v_cndmask_b32_e32 v86, v229, v86, vcc
	v_lshlrev_b32_e32 v86, 2, v86
	ds_bpermute_b32 v86, v86, v2
	s_waitcnt lgkmcnt(0)
	v_add_f32_e32 v2, v2, v86
	v_xor_b32_e32 v86, 32, v229
	v_cmp_lt_i32_e32 vcc, v86, v87
	s_nop 1
	v_cndmask_b32_e32 v86, v229, v86, vcc
	v_lshlrev_b32_e32 v97, 2, v86
	ds_bpermute_b32 v86, v97, v2
	s_waitcnt lgkmcnt(0)
	v_add_f32_e32 v2, v2, v86
	v_fmamk_f32 v2, v2, 0x3c800000, v226
	v_cmp_gt_f32_e32 vcc, s11, v2
	v_mul_f32_e32 v86, 0x4b800000, v2
	s_nop 0
	v_cndmask_b32_e32 v2, v2, v86, vcc
	v_rsq_f32_e32 v2, v2
	s_nop 0
	v_mul_f32_e32 v86, 0x45800000, v2
	v_cndmask_b32_e32 v2, v2, v86, vcc
	v_mul_f32_e32 v80, v80, v2
	v_mul_f32_e32 v81, v81, v2
	v_mul_f32_e32 v82, v82, v2
	v_mul_f32_e32 v83, v83, v2
	v_mul_f32_e32 v78, v78, v2
	v_mul_f32_e32 v79, v79, v2
	v_mul_f32_e32 v76, v76, v2
	v_mul_f32_e32 v77, v77, v2
	v_mul_f32_e32 v74, v74, v2
	v_mul_f32_e32 v75, v75, v2
	v_mul_f32_e32 v72, v72, v2
	v_mul_f32_e32 v73, v73, v2
	v_mul_f32_e32 v70, v70, v2
	v_mul_f32_e32 v71, v71, v2
	v_mul_f32_e32 v68, v68, v2
	v_mul_f32_e32 v69, v69, v2
	v_lshlrev_b32_e32 v2, 2, v85
	s_waitcnt vmcnt(0)
	v_mul_f32_e32 v92, v32, v80
	v_mul_f32_e32 v93, v33, v81
	v_mul_f32_e32 v80, v24, v72
	v_mul_f32_e32 v81, v25, v73
	v_lshl_add_u64 v[72:73], v[154:155], 0, v[2:3]
	v_mul_f32_e32 v90, v34, v82
	v_mul_f32_e32 v91, v35, v83
	v_mul_f32_e32 v86, v28, v76
	v_mul_f32_e32 v87, v29, v77
	v_mul_f32_e32 v88, v30, v78
	v_mul_f32_e32 v89, v31, v79
	v_mul_f32_e32 v82, v26, v74
	v_mul_f32_e32 v83, v27, v75
	v_mul_f32_e32 v76, v20, v68
	v_mul_f32_e32 v77, v21, v69
	v_mul_f32_e32 v78, v22, v70
	v_mul_f32_e32 v79, v23, v71
	global_load_dwordx4 v[68:71], v[72:73], off offset:16
	s_nop 0
	global_load_dwordx4 v[72:75], v[72:73], off
	ds_bpermute_b32 v94, v97, v92
	ds_bpermute_b32 v95, v97, v93
	ds_bpermute_b32 v96, v97, v90
	ds_bpermute_b32 v97, v97, v91
	v_ashrrev_i32_e32 v85, 31, v84
	s_waitcnt vmcnt(1)
	v_mov_b32_e32 v98, v69
	v_mov_b32_e32 v99, v71
	s_waitcnt lgkmcnt(0)
	v_mul_f32_e32 v96, v98, v96
	v_mul_f32_e32 v97, v99, v97
	s_waitcnt vmcnt(0)
	v_mov_b32_e32 v98, v73
	v_mov_b32_e32 v99, v75
	v_mul_f32_e32 v94, v98, v94
	v_mul_f32_e32 v95, v99, v95
	v_xor_b32_e32 v71, 0x80000000, v96
	v_xor_b32_e32 v2, 0x80000000, v94
	v_xor_b32_e32 v69, 0x80000000, v95
	v_xor_b32_e32 v73, 0x80000000, v97
	v_cndmask_b32_e64 v97, v97, v73, s[4:5]
	v_cndmask_b32_e64 v96, v96, v71, s[4:5]
	v_cndmask_b32_e64 v95, v95, v69, s[4:5]
	v_cndmask_b32_e64 v94, v94, v2, s[4:5]
	v_mov_b32_e32 v73, v74
	v_mov_b32_e32 v69, v70
	v_lshlrev_b64 v[70:71], 11, v[84:85]
	v_fma_f32 v72, v72, v92, v94
	v_fma_f32 v73, v73, v93, v95
	v_lshl_add_u64 v[70:71], s[8:9], 0, v[70:71]
	v_fma_f32 v68, v68, v90, v96
	v_fma_f32 v69, v69, v91, v97
	v_lshl_add_u64 v[70:71], s[24:25], 1, v[70:71]
	v_lshlrev_b32_e32 v2, 1, v152
	v_mul_f32_e32 v72, s30, v72
	v_mul_f32_e32 v73, s30, v73
	v_lshl_add_u64 v[70:71], v[70:71], 0, v[2:3]
	v_mul_f32_e32 v68, s30, v68
	v_mul_f32_e32 v69, s30, v69
	v_cvt_pk_bf16_f32 v72, v72, v73
	s_nop 0
	v_cvt_pk_bf16_f32 v73, v68, v69
	global_store_dwordx2 v[70:71], v[72:73], off
	v_mul_f32_e32 v72, s30, v86
	v_mul_f32_e32 v73, s30, v87
	v_mul_f32_e32 v68, s30, v88
	v_mul_f32_e32 v69, s30, v89
	v_cvt_pk_bf16_f32 v72, v72, v73
	s_nop 0
	v_cvt_pk_bf16_f32 v73, v68, v69
	global_store_dwordx2 v[70:71], v[72:73], off offset:32
	v_mul_f32_e32 v72, s30, v80
	v_mul_f32_e32 v73, s30, v81
	v_mul_f32_e32 v68, s30, v82
	v_mul_f32_e32 v69, s30, v83
	v_cvt_pk_bf16_f32 v72, v72, v73
	s_nop 0
	v_cvt_pk_bf16_f32 v73, v68, v69
	global_store_dwordx2 v[70:71], v[72:73], off offset:64
	v_mul_f32_e32 v72, s30, v76
	v_mul_f32_e32 v73, s30, v77
	v_mul_f32_e32 v68, s30, v78
	v_mul_f32_e32 v69, s30, v79
	v_cvt_pk_bf16_f32 v72, v72, v73
	s_nop 0
	v_cvt_pk_bf16_f32 v73, v68, v69
	global_store_dwordx2 v[70:71], v[72:73], off offset:96

.LBB0_488:
	s_andn2_b64 vcc, exec, s[30:31]
	s_cbranch_vccnz .LBB0_490
	v_mul_f32_e32 v70, v66, v66
	v_mul_f32_e32 v71, v67, v67
	v_mul_f32_e32 v72, v64, v64
	v_mul_f32_e32 v73, v65, v65
	s_movk_i32 s11, 0x4000
	v_pk_mov_b32 v[74:75], v[72:73], v[70:71] op_sel:[1,0]
	v_mov_b32_e32 v73, v71
	v_add_f32_e32 v70, v74, v72
	v_add_f32_e32 v71, v75, v73
	v_mul_f32_e32 v72, v62, v62
	v_mul_f32_e32 v73, v63, v63
	v_mul_f32_e32 v74, v60, v60
	v_mul_f32_e32 v75, v61, v61
	v_lshlrev_b32_e32 v2, 4, v68
	v_pk_mov_b32 v[76:77], v[74:75], v[72:73] op_sel:[1,0]
	v_mov_b32_e32 v75, v73
	v_cmp_gt_i32_e32 vcc, s11, v68
	v_and_b32_e32 v2, 0x1fdf0, v2
	v_add_f32_e32 v72, v76, v74
	v_add_f32_e32 v73, v77, v75
	v_cndmask_b32_e32 v69, v230, v2, vcc
	v_mul_f32_e32 v2, v52, v52
	v_mul_f32_e32 v74, v53, v53
	v_add_f32_e32 v70, v70, v71
	v_mov_b32_e32 v71, v70
	v_add_f32_e32 v72, v72, v73
	v_mov_b32_e32 v73, v72
	v_mov_b32_e32 v71, v2
	v_mov_b32_e32 v73, v74
	v_mul_f32_e32 v2, v57, v57
	v_mul_f32_e32 v75, v54, v54
	v_add_f32_e32 v70, v70, v72
	v_add_f32_e32 v71, v71, v73
	v_fma_f32 v72, v56, v56, v2
	v_fma_f32 v73, v57, v57, v2
	v_mul_f32_e32 v2, v59, v59
	v_mul_f32_e32 v76, v55, v55
	v_mov_b32_e32 v73, v75
	v_fma_f32 v74, v58, v58, v2
	v_fma_f32 v75, v59, v59, v2
	s_mov_b32 s11, 0x800000
	v_mov_b32_e32 v75, v76
	v_add_f32_e32 v72, v72, v74
	v_add_f32_e32 v73, v73, v75
	s_mov_b32 s30, 0x3e38aa3b
	v_add_f32_e32 v70, v70, v72
	v_add_f32_e32 v71, v71, v73
	s_nop 0
	v_add_f32_e32 v2, v70, v71
	v_and_b32_e32 v71, 64, v229
	v_xor_b32_e32 v70, 16, v229
	v_add_u32_e32 v71, 64, v71
	v_cmp_lt_i32_e32 vcc, v70, v71
	s_nop 1
	v_cndmask_b32_e32 v70, v229, v70, vcc
	v_lshlrev_b32_e32 v70, 2, v70
	ds_bpermute_b32 v70, v70, v2
	s_waitcnt lgkmcnt(0)
	v_add_f32_e32 v2, v2, v70
	v_xor_b32_e32 v70, 32, v229
	v_cmp_lt_i32_e32 vcc, v70, v71
	s_nop 1
	v_cndmask_b32_e32 v70, v229, v70, vcc
	v_lshlrev_b32_e32 v81, 2, v70
	ds_bpermute_b32 v70, v81, v2
	s_waitcnt lgkmcnt(0)
	v_add_f32_e32 v2, v2, v70
	v_fmamk_f32 v2, v2, 0x3c800000, v226
	v_cmp_gt_f32_e32 vcc, s11, v2
	v_mul_f32_e32 v70, 0x4b800000, v2
	s_nop 0
	v_cndmask_b32_e32 v2, v2, v70, vcc
	v_rsq_f32_e32 v2, v2
	s_nop 0
	v_mul_f32_e32 v70, 0x45800000, v2
	v_cndmask_b32_e32 v2, v2, v70, vcc
	v_mul_f32_e32 v64, v64, v2
	v_mul_f32_e32 v65, v65, v2
	v_mul_f32_e32 v66, v66, v2
	v_mul_f32_e32 v67, v67, v2
	v_mul_f32_e32 v62, v62, v2
	v_mul_f32_e32 v63, v63, v2
	v_mul_f32_e32 v60, v60, v2
	v_mul_f32_e32 v61, v61, v2
	v_mul_f32_e32 v58, v58, v2
	v_mul_f32_e32 v59, v59, v2
	v_mul_f32_e32 v56, v56, v2
	v_mul_f32_e32 v57, v57, v2
	v_mul_f32_e32 v54, v54, v2
	v_mul_f32_e32 v55, v55, v2
	v_mul_f32_e32 v52, v52, v2
	v_mul_f32_e32 v53, v53, v2
	v_lshlrev_b32_e32 v2, 2, v69
	s_waitcnt vmcnt(0)
	v_mul_f32_e32 v76, v32, v64
	v_mul_f32_e32 v77, v33, v65
	v_mul_f32_e32 v64, v24, v56
	v_mul_f32_e32 v65, v25, v57
	v_lshl_add_u64 v[56:57], v[154:155], 0, v[2:3]
	v_mul_f32_e32 v74, v34, v66
	v_mul_f32_e32 v75, v35, v67
	v_mul_f32_e32 v70, v28, v60
	v_mul_f32_e32 v71, v29, v61
	v_mul_f32_e32 v72, v30, v62
	v_mul_f32_e32 v73, v31, v63
	v_mul_f32_e32 v66, v26, v58
	v_mul_f32_e32 v67, v27, v59
	v_mul_f32_e32 v60, v20, v52
	v_mul_f32_e32 v61, v21, v53
	v_mul_f32_e32 v62, v22, v54
	v_mul_f32_e32 v63, v23, v55
	global_load_dwordx4 v[52:55], v[56:57], off offset:16
	s_nop 0
	global_load_dwordx4 v[56:59], v[56:57], off
	ds_bpermute_b32 v78, v81, v76
	ds_bpermute_b32 v79, v81, v77
	ds_bpermute_b32 v80, v81, v74
	ds_bpermute_b32 v81, v81, v75
	v_ashrrev_i32_e32 v69, 31, v68
	s_waitcnt vmcnt(1)
	v_mov_b32_e32 v82, v53
	v_mov_b32_e32 v83, v55
	s_waitcnt lgkmcnt(0)
	v_mul_f32_e32 v80, v82, v80
	v_mul_f32_e32 v81, v83, v81
	s_waitcnt vmcnt(0)
	v_mov_b32_e32 v82, v57
	v_mov_b32_e32 v83, v59
	v_mul_f32_e32 v78, v82, v78
	v_mul_f32_e32 v79, v83, v79
	v_xor_b32_e32 v55, 0x80000000, v80
	v_xor_b32_e32 v2, 0x80000000, v78
	v_xor_b32_e32 v53, 0x80000000, v79
	v_xor_b32_e32 v57, 0x80000000, v81
	v_cndmask_b32_e64 v81, v81, v57, s[4:5]
	v_cndmask_b32_e64 v80, v80, v55, s[4:5]
	v_cndmask_b32_e64 v79, v79, v53, s[4:5]
	v_cndmask_b32_e64 v78, v78, v2, s[4:5]
	v_mov_b32_e32 v57, v58
	v_mov_b32_e32 v53, v54
	v_lshlrev_b64 v[54:55], 11, v[68:69]
	v_fma_f32 v56, v56, v76, v78
	v_fma_f32 v57, v57, v77, v79
	v_lshl_add_u64 v[54:55], s[8:9], 0, v[54:55]
	v_fma_f32 v52, v52, v74, v80
	v_fma_f32 v53, v53, v75, v81
	v_lshl_add_u64 v[54:55], s[24:25], 1, v[54:55]
	v_lshlrev_b32_e32 v2, 1, v152
	v_mul_f32_e32 v56, s30, v56
	v_mul_f32_e32 v57, s30, v57
	v_lshl_add_u64 v[54:55], v[54:55], 0, v[2:3]
	v_mul_f32_e32 v52, s30, v52
	v_mul_f32_e32 v53, s30, v53
	v_cvt_pk_bf16_f32 v56, v56, v57
	s_nop 0
	v_cvt_pk_bf16_f32 v57, v52, v53
	global_store_dwordx2 v[54:55], v[56:57], off
	v_mul_f32_e32 v56, s30, v70
	v_mul_f32_e32 v57, s30, v71
	v_mul_f32_e32 v52, s30, v72
	v_mul_f32_e32 v53, s30, v73
	v_cvt_pk_bf16_f32 v56, v56, v57
	s_nop 0
	v_cvt_pk_bf16_f32 v57, v52, v53
	global_store_dwordx2 v[54:55], v[56:57], off offset:32
	v_mul_f32_e32 v56, s30, v64
	v_mul_f32_e32 v57, s30, v65
	v_mul_f32_e32 v52, s30, v66
	v_mul_f32_e32 v53, s30, v67
	v_cvt_pk_bf16_f32 v56, v56, v57
	s_nop 0
	v_cvt_pk_bf16_f32 v57, v52, v53
	global_store_dwordx2 v[54:55], v[56:57], off offset:64
	v_mul_f32_e32 v56, s30, v60
	v_mul_f32_e32 v57, s30, v61
	v_mul_f32_e32 v52, s30, v62
	v_mul_f32_e32 v53, s30, v63
	v_cvt_pk_bf16_f32 v56, v56, v57
	s_nop 0
	v_cvt_pk_bf16_f32 v57, v52, v53
	global_store_dwordx2 v[54:55], v[56:57], off offset:96

.LBB0_496:
	s_andn2_b64 vcc, exec, s[30:31]
	s_cbranch_vccnz .LBB0_498
	v_mul_f32_e32 v54, v50, v50
	v_mul_f32_e32 v55, v51, v51
	v_mul_f32_e32 v56, v48, v48
	v_mul_f32_e32 v57, v49, v49
	s_movk_i32 s11, 0x4000
	v_pk_mov_b32 v[58:59], v[56:57], v[54:55] op_sel:[1,0]
	v_mov_b32_e32 v57, v55
	v_add_f32_e32 v54, v58, v56
	v_add_f32_e32 v55, v59, v57
	v_mul_f32_e32 v56, v46, v46
	v_mul_f32_e32 v57, v47, v47
	v_mul_f32_e32 v58, v44, v44
	v_mul_f32_e32 v59, v45, v45
	v_lshlrev_b32_e32 v2, 4, v52
	v_pk_mov_b32 v[60:61], v[58:59], v[56:57] op_sel:[1,0]
	v_mov_b32_e32 v59, v57
	v_cmp_gt_i32_e32 vcc, s11, v52
	v_and_b32_e32 v2, 0x1fef0, v2
	v_add_f32_e32 v56, v60, v58
	v_add_f32_e32 v57, v61, v59
	v_cndmask_b32_e32 v53, v230, v2, vcc
	v_mul_f32_e32 v2, v36, v36
	v_mul_f32_e32 v58, v37, v37
	v_add_f32_e32 v54, v54, v55
	v_mov_b32_e32 v55, v54
	v_add_f32_e32 v56, v56, v57
	v_mov_b32_e32 v57, v56
	v_mov_b32_e32 v55, v2
	v_mov_b32_e32 v57, v58
	v_mul_f32_e32 v2, v41, v41
	v_mul_f32_e32 v59, v38, v38
	v_add_f32_e32 v54, v54, v56
	v_add_f32_e32 v55, v55, v57
	v_fma_f32 v56, v40, v40, v2
	v_fma_f32 v57, v41, v41, v2
	v_mul_f32_e32 v2, v43, v43
	v_mul_f32_e32 v60, v39, v39
	v_mov_b32_e32 v57, v59
	v_fma_f32 v58, v42, v42, v2
	v_fma_f32 v59, v43, v43, v2
	s_mov_b32 s11, 0x800000
	v_mov_b32_e32 v59, v60
	v_add_f32_e32 v56, v56, v58
	v_add_f32_e32 v57, v57, v59
	s_mov_b32 s30, 0x3e38aa3b
	v_add_f32_e32 v54, v54, v56
	v_add_f32_e32 v55, v55, v57
	s_nop 0
	v_add_f32_e32 v2, v54, v55
	v_and_b32_e32 v55, 64, v229
	v_xor_b32_e32 v54, 16, v229
	v_add_u32_e32 v55, 64, v55
	v_cmp_lt_i32_e32 vcc, v54, v55
	s_nop 1
	v_cndmask_b32_e32 v54, v229, v54, vcc
	v_lshlrev_b32_e32 v54, 2, v54
	ds_bpermute_b32 v54, v54, v2
	s_waitcnt lgkmcnt(0)
	v_add_f32_e32 v2, v2, v54
	v_xor_b32_e32 v54, 32, v229
	v_cmp_lt_i32_e32 vcc, v54, v55
	s_nop 1
	v_cndmask_b32_e32 v54, v229, v54, vcc
	v_lshlrev_b32_e32 v65, 2, v54
	ds_bpermute_b32 v54, v65, v2
	s_waitcnt lgkmcnt(0)
	v_add_f32_e32 v2, v2, v54
	v_fmamk_f32 v2, v2, 0x3c800000, v226
	v_cmp_gt_f32_e32 vcc, s11, v2
	v_mul_f32_e32 v54, 0x4b800000, v2
	s_nop 0
	v_cndmask_b32_e32 v2, v2, v54, vcc
	v_rsq_f32_e32 v2, v2
	s_nop 0
	v_mul_f32_e32 v54, 0x45800000, v2
	v_cndmask_b32_e32 v2, v2, v54, vcc
	v_mul_f32_e32 v48, v48, v2
	v_mul_f32_e32 v49, v49, v2
	v_mul_f32_e32 v50, v50, v2
	v_mul_f32_e32 v51, v51, v2
	v_mul_f32_e32 v46, v46, v2
	v_mul_f32_e32 v47, v47, v2
	v_mul_f32_e32 v44, v44, v2
	v_mul_f32_e32 v45, v45, v2
	v_mul_f32_e32 v42, v42, v2
	v_mul_f32_e32 v43, v43, v2
	v_mul_f32_e32 v40, v40, v2
	v_mul_f32_e32 v41, v41, v2
	v_mul_f32_e32 v38, v38, v2
	v_mul_f32_e32 v39, v39, v2
	v_mul_f32_e32 v36, v36, v2
	v_mul_f32_e32 v37, v37, v2
	v_lshlrev_b32_e32 v2, 2, v53
	s_waitcnt vmcnt(0)
	v_mul_f32_e32 v60, v32, v48
	v_mul_f32_e32 v61, v33, v49
	v_mul_f32_e32 v48, v24, v40
	v_mul_f32_e32 v49, v25, v41
	v_lshl_add_u64 v[40:41], v[154:155], 0, v[2:3]
	v_mul_f32_e32 v58, v34, v50
	v_mul_f32_e32 v59, v35, v51
	v_mul_f32_e32 v54, v28, v44
	v_mul_f32_e32 v55, v29, v45
	v_mul_f32_e32 v56, v30, v46
	v_mul_f32_e32 v57, v31, v47
	v_mul_f32_e32 v50, v26, v42
	v_mul_f32_e32 v51, v27, v43
	v_mul_f32_e32 v44, v20, v36
	v_mul_f32_e32 v45, v21, v37
	v_mul_f32_e32 v46, v22, v38
	v_mul_f32_e32 v47, v23, v39
	global_load_dwordx4 v[36:39], v[40:41], off offset:16
	s_nop 0
	global_load_dwordx4 v[40:43], v[40:41], off
	ds_bpermute_b32 v62, v65, v60
	ds_bpermute_b32 v63, v65, v61
	ds_bpermute_b32 v64, v65, v58
	ds_bpermute_b32 v65, v65, v59
	v_ashrrev_i32_e32 v53, 31, v52
	s_waitcnt vmcnt(1)
	v_mov_b32_e32 v66, v37
	v_mov_b32_e32 v67, v39
	s_waitcnt lgkmcnt(0)
	v_mul_f32_e32 v64, v66, v64
	v_mul_f32_e32 v65, v67, v65
	s_waitcnt vmcnt(0)
	v_mov_b32_e32 v66, v41
	v_mov_b32_e32 v67, v43
	v_mul_f32_e32 v62, v66, v62
	v_mul_f32_e32 v63, v67, v63
	v_xor_b32_e32 v39, 0x80000000, v64
	v_xor_b32_e32 v2, 0x80000000, v62
	v_xor_b32_e32 v37, 0x80000000, v63
	v_xor_b32_e32 v41, 0x80000000, v65
	v_cndmask_b32_e64 v65, v65, v41, s[4:5]
	v_cndmask_b32_e64 v64, v64, v39, s[4:5]
	v_cndmask_b32_e64 v63, v63, v37, s[4:5]
	v_cndmask_b32_e64 v62, v62, v2, s[4:5]
	v_mov_b32_e32 v41, v42
	v_mov_b32_e32 v37, v38
	v_lshlrev_b64 v[38:39], 11, v[52:53]
	v_fma_f32 v40, v40, v60, v62
	v_fma_f32 v41, v41, v61, v63
	v_lshl_add_u64 v[38:39], s[8:9], 0, v[38:39]
	v_fma_f32 v36, v36, v58, v64
	v_fma_f32 v37, v37, v59, v65
	v_lshl_add_u64 v[38:39], s[24:25], 1, v[38:39]
	v_lshlrev_b32_e32 v2, 1, v152
	v_mul_f32_e32 v40, s30, v40
	v_mul_f32_e32 v41, s30, v41
	v_lshl_add_u64 v[38:39], v[38:39], 0, v[2:3]
	v_mul_f32_e32 v36, s30, v36
	v_mul_f32_e32 v37, s30, v37
	v_cvt_pk_bf16_f32 v40, v40, v41
	s_nop 0
	v_cvt_pk_bf16_f32 v41, v36, v37
	global_store_dwordx2 v[38:39], v[40:41], off
	v_mul_f32_e32 v40, s30, v54
	v_mul_f32_e32 v41, s30, v55
	v_mul_f32_e32 v36, s30, v56
	v_mul_f32_e32 v37, s30, v57
	v_cvt_pk_bf16_f32 v40, v40, v41
	s_nop 0
	v_cvt_pk_bf16_f32 v41, v36, v37
	global_store_dwordx2 v[38:39], v[40:41], off offset:32
	v_mul_f32_e32 v40, s30, v48
	v_mul_f32_e32 v41, s30, v49
	v_mul_f32_e32 v36, s30, v50
	v_mul_f32_e32 v37, s30, v51
	v_cvt_pk_bf16_f32 v40, v40, v41
	s_nop 0
	v_cvt_pk_bf16_f32 v41, v36, v37
	global_store_dwordx2 v[38:39], v[40:41], off offset:64
	v_mul_f32_e32 v40, s30, v44
	v_mul_f32_e32 v41, s30, v45
	v_mul_f32_e32 v36, s30, v46
	v_mul_f32_e32 v37, s30, v47
	v_cvt_pk_bf16_f32 v40, v40, v41
	s_nop 0
	v_cvt_pk_bf16_f32 v41, v36, v37
	global_store_dwordx2 v[38:39], v[40:41], off offset:96

.LBB0_504:
	s_andn2_b64 vcc, exec, s[26:27]
	s_cbranch_vccnz .LBB0_506
	v_mul_f32_e32 v38, v18, v18
	v_mul_f32_e32 v39, v19, v19
	v_mul_f32_e32 v40, v16, v16
	v_mul_f32_e32 v41, v17, v17
	s_movk_i32 s11, 0x4000
	v_pk_mov_b32 v[42:43], v[40:41], v[38:39] op_sel:[1,0]
	v_mov_b32_e32 v41, v39
	v_add_f32_e32 v38, v42, v40
	v_add_f32_e32 v39, v43, v41
	v_mul_f32_e32 v40, v14, v14
	v_mul_f32_e32 v41, v15, v15
	v_mul_f32_e32 v42, v12, v12
	v_mul_f32_e32 v43, v13, v13
	v_lshlrev_b32_e32 v2, 4, v36
	v_pk_mov_b32 v[44:45], v[42:43], v[40:41] op_sel:[1,0]
	v_mov_b32_e32 v43, v41
	v_cmp_gt_i32_e32 vcc, s11, v36
	v_and_b32_e32 v2, 0x1fff0, v2
	v_add_f32_e32 v40, v44, v42
	v_add_f32_e32 v41, v45, v43
	v_cndmask_b32_e32 v37, v230, v2, vcc
	v_mul_f32_e32 v2, v4, v4
	v_mul_f32_e32 v42, v5, v5
	v_add_f32_e32 v38, v38, v39
	v_mov_b32_e32 v39, v38
	v_add_f32_e32 v40, v40, v41
	v_mov_b32_e32 v41, v40
	v_mov_b32_e32 v39, v2
	v_mov_b32_e32 v41, v42
	v_mul_f32_e32 v2, v9, v9
	v_mul_f32_e32 v43, v6, v6
	v_add_f32_e32 v38, v38, v40
	v_add_f32_e32 v39, v39, v41
	v_fma_f32 v40, v8, v8, v2
	v_fma_f32 v41, v9, v9, v2
	v_mul_f32_e32 v2, v11, v11
	v_mul_f32_e32 v44, v7, v7
	v_mov_b32_e32 v41, v43
	v_fma_f32 v42, v10, v10, v2
	v_fma_f32 v43, v11, v11, v2
	s_mov_b32 s11, 0x800000
	v_mov_b32_e32 v43, v44
	v_add_f32_e32 v40, v40, v42
	v_add_f32_e32 v41, v41, v43
	s_nop 0
	v_add_f32_e32 v38, v38, v40
	v_add_f32_e32 v39, v39, v41
	s_nop 0
	v_add_f32_e32 v2, v38, v39
	v_and_b32_e32 v39, 64, v229
	v_xor_b32_e32 v38, 16, v229
	v_add_u32_e32 v39, 64, v39
	v_cmp_lt_i32_e32 vcc, v38, v39
	s_nop 1
	v_cndmask_b32_e32 v38, v229, v38, vcc
	v_lshlrev_b32_e32 v38, 2, v38
	ds_bpermute_b32 v38, v38, v2
	s_waitcnt lgkmcnt(0)
	v_add_f32_e32 v2, v2, v38
	v_xor_b32_e32 v38, 32, v229
	v_cmp_lt_i32_e32 vcc, v38, v39
	s_nop 1
	v_cndmask_b32_e32 v38, v229, v38, vcc
	v_lshlrev_b32_e32 v38, 2, v38
	ds_bpermute_b32 v39, v38, v2
	s_waitcnt lgkmcnt(0)
	v_add_f32_e32 v2, v2, v39
	v_fmamk_f32 v2, v2, 0x3c800000, v226
	v_cmp_gt_f32_e32 vcc, s11, v2
	v_mul_f32_e32 v39, 0x4b800000, v2
	s_nop 0
	v_cndmask_b32_e32 v2, v2, v39, vcc
	v_rsq_f32_e32 v2, v2
	s_nop 0
	v_mul_f32_e32 v39, 0x45800000, v2
	v_cndmask_b32_e32 v2, v2, v39, vcc
	v_mul_f32_e32 v16, v16, v2
	v_mul_f32_e32 v17, v17, v2
	v_mul_f32_e32 v18, v18, v2
	v_mul_f32_e32 v19, v19, v2
	v_mul_f32_e32 v14, v14, v2
	v_mul_f32_e32 v15, v15, v2
	v_mul_f32_e32 v12, v12, v2
	v_mul_f32_e32 v13, v13, v2
	v_mul_f32_e32 v10, v10, v2
	v_mul_f32_e32 v11, v11, v2
	v_mul_f32_e32 v8, v8, v2
	v_mul_f32_e32 v9, v9, v2
	v_mul_f32_e32 v6, v6, v2
	v_mul_f32_e32 v7, v7, v2
	v_mul_f32_e32 v4, v4, v2
	v_mul_f32_e32 v5, v5, v2
	v_lshlrev_b32_e32 v2, 2, v37
	s_waitcnt vmcnt(0)
	v_mul_f32_e32 v32, v32, v16
	v_mul_f32_e32 v33, v33, v17
	v_mul_f32_e32 v16, v24, v8
	v_mul_f32_e32 v17, v25, v9
	v_lshl_add_u64 v[8:9], v[154:155], 0, v[2:3]
	v_mul_f32_e32 v34, v34, v18
	v_mul_f32_e32 v35, v35, v19
	v_mul_f32_e32 v28, v28, v12
	v_mul_f32_e32 v29, v29, v13
	v_mul_f32_e32 v30, v30, v14
	v_mul_f32_e32 v31, v31, v15
	v_mul_f32_e32 v18, v26, v10
	v_mul_f32_e32 v19, v27, v11
	v_mul_f32_e32 v12, v20, v4
	v_mul_f32_e32 v13, v21, v5
	v_mul_f32_e32 v14, v22, v6
	v_mul_f32_e32 v15, v23, v7
	global_load_dwordx4 v[4:7], v[8:9], off offset:16
	s_nop 0
	global_load_dwordx4 v[8:11], v[8:9], off
	ds_bpermute_b32 v22, v38, v34
	ds_bpermute_b32 v23, v38, v35
	ds_bpermute_b32 v20, v38, v32
	ds_bpermute_b32 v21, v38, v33
	v_ashrrev_i32_e32 v37, 31, v36
	s_waitcnt vmcnt(1)
	v_mov_b32_e32 v24, v5
	v_mov_b32_e32 v25, v7
	s_waitcnt lgkmcnt(2)
	v_mul_f32_e32 v22, v24, v22
	v_mul_f32_e32 v23, v25, v23
	s_waitcnt vmcnt(0)
	v_mov_b32_e32 v24, v9
	v_mov_b32_e32 v25, v11
	s_waitcnt lgkmcnt(0)
	v_mul_f32_e32 v20, v24, v20
	v_mul_f32_e32 v21, v25, v21
	v_xor_b32_e32 v7, 0x80000000, v22
	v_xor_b32_e32 v5, 0x80000000, v21
	v_xor_b32_e32 v2, 0x80000000, v20
	v_xor_b32_e32 v9, 0x80000000, v23
	v_cndmask_b32_e64 v22, v22, v7, s[4:5]
	v_cndmask_b32_e64 v21, v21, v5, s[4:5]
	v_mov_b32_e32 v5, v6
	v_lshlrev_b64 v[6:7], 11, v[36:37]
	v_cndmask_b32_e64 v23, v23, v9, s[4:5]
	v_cndmask_b32_e64 v20, v20, v2, s[4:5]
	v_mov_b32_e32 v9, v10
	v_lshl_add_u64 v[6:7], s[8:9], 0, v[6:7]
	v_fma_f32 v8, v8, v32, v20
	v_fma_f32 v9, v9, v33, v21
	v_lshl_add_u64 v[6:7], s[24:25], 1, v[6:7]
	s_mov_b32 s24, 0x3e38aa3b
	v_fma_f32 v4, v4, v34, v22
	v_fma_f32 v5, v5, v35, v23
	v_lshlrev_b32_e32 v2, 1, v152
	v_mul_f32_e32 v8, s24, v8
	v_mul_f32_e32 v9, s24, v9
	v_lshl_add_u64 v[6:7], v[6:7], 0, v[2:3]
	v_mul_f32_e32 v4, s24, v4
	v_mul_f32_e32 v5, s24, v5
	v_cvt_pk_bf16_f32 v8, v8, v9
	s_nop 0
	v_cvt_pk_bf16_f32 v9, v4, v5
	global_store_dwordx2 v[6:7], v[8:9], off
	v_mul_f32_e32 v8, s24, v28
	v_mul_f32_e32 v9, s24, v29
	v_mul_f32_e32 v4, s24, v30
	v_mul_f32_e32 v5, s24, v31
	v_cvt_pk_bf16_f32 v8, v8, v9
	s_nop 0
	v_cvt_pk_bf16_f32 v9, v4, v5
	global_store_dwordx2 v[6:7], v[8:9], off offset:32
	v_mul_f32_e32 v8, s24, v16
	v_mul_f32_e32 v9, s24, v17
	v_mul_f32_e32 v4, s24, v18
	v_mul_f32_e32 v5, s24, v19
	v_cvt_pk_bf16_f32 v8, v8, v9
	s_nop 0
	v_cvt_pk_bf16_f32 v9, v4, v5
	global_store_dwordx2 v[6:7], v[8:9], off offset:64
	v_mul_f32_e32 v8, s24, v12
	v_mul_f32_e32 v9, s24, v13
	v_mul_f32_e32 v4, s24, v14
	v_mul_f32_e32 v5, s24, v15
	v_cvt_pk_bf16_f32 v8, v8, v9
	s_nop 0
	v_cvt_pk_bf16_f32 v9, v4, v5
	global_store_dwordx2 v[6:7], v[8:9], off offset:96
